# k5 plus adaLN GEMV-partial inner loops software-pipelined 4 deep (24 row loads in flight instead of draining 8 per step); shortens the layer-0 in-proj tail work and prologue A
# speedup vs baseline: 1.0010x; 1.0010x over previous
.LBB0_420:
	v_mov_b32_e32 v214, s18
	v_mov_b32_e32 v215, 0
	v_lshl_add_u64 v[200:201], v[16:17], 0, v[214:215]
	v_mov_b32_e32 v214, s19
	v_mov_b32_e32 v215, 0
	v_lshl_add_u64 v[202:203], v[16:17], 0, v[214:215]
	v_mov_b32_e32 v214, s20
	v_mov_b32_e32 v215, 0
	v_lshl_add_u64 v[204:205], v[16:17], 0, v[214:215]
	v_mov_b32_e32 v214, s21
	v_mov_b32_e32 v215, 0
	v_lshl_add_u64 v[206:207], v[16:17], 0, v[214:215]
	v_mov_b32_e32 v214, s22
	v_mov_b32_e32 v215, 0
	v_lshl_add_u64 v[208:209], v[16:17], 0, v[214:215]
	v_mov_b32_e32 v214, s23
	v_mov_b32_e32 v215, 0
	v_lshl_add_u64 v[210:211], v[16:17], 0, v[214:215]
	v_mov_b32_e32 v214, s26
	v_mov_b32_e32 v215, 0
	v_lshl_add_u64 v[212:213], v[16:17], 0, v[214:215]
	s_mov_b64 s[98:99], 0
	v_lshl_add_u64 v[20:21], v[16:17], 0, s[98:99]
	global_load_dwordx4 v[18:21], v[20:21], off
	v_lshl_add_u64 v[24:25], v[200:201], 0, s[98:99]
	global_load_dwordx4 v[22:25], v[24:25], off
	v_lshl_add_u64 v[28:29], v[202:203], 0, s[98:99]
	global_load_dwordx4 v[26:29], v[28:29], off
	v_lshl_add_u64 v[32:33], v[204:205], 0, s[98:99]
	global_load_dwordx4 v[30:33], v[32:33], off
	v_lshl_add_u64 v[36:37], v[206:207], 0, s[98:99]
	global_load_dwordx4 v[34:37], v[36:37], off
	v_lshl_add_u64 v[40:41], v[208:209], 0, s[98:99]
	global_load_dwordx4 v[38:41], v[40:41], off
	v_lshl_add_u64 v[44:45], v[210:211], 0, s[98:99]
	global_load_dwordx4 v[42:45], v[44:45], off
	v_lshl_add_u64 v[48:49], v[212:213], 0, s[98:99]
	global_load_dwordx4 v[46:49], v[48:49], off
	s_add_u32 s98, s98, 0x60000
	s_addc_u32 s99, s99, 0
	v_lshl_add_u64 v[106:107], v[16:17], 0, s[98:99]
	global_load_dwordx4 v[104:107], v[106:107], off
	v_lshl_add_u64 v[110:111], v[200:201], 0, s[98:99]
	global_load_dwordx4 v[108:111], v[110:111], off
	v_lshl_add_u64 v[114:115], v[202:203], 0, s[98:99]
	global_load_dwordx4 v[112:115], v[114:115], off
	v_lshl_add_u64 v[118:119], v[204:205], 0, s[98:99]
	global_load_dwordx4 v[116:119], v[118:119], off
	v_lshl_add_u64 v[122:123], v[206:207], 0, s[98:99]
	global_load_dwordx4 v[120:123], v[122:123], off
	v_lshl_add_u64 v[126:127], v[208:209], 0, s[98:99]
	global_load_dwordx4 v[124:127], v[126:127], off
	v_lshl_add_u64 v[130:131], v[210:211], 0, s[98:99]
	global_load_dwordx4 v[128:131], v[130:131], off
	v_lshl_add_u64 v[134:135], v[212:213], 0, s[98:99]
	global_load_dwordx4 v[132:135], v[134:135], off
	s_add_u32 s98, s98, 0x60000
	s_addc_u32 s99, s99, 0
	v_lshl_add_u64 v[138:139], v[16:17], 0, s[98:99]
	global_load_dwordx4 v[136:139], v[138:139], off
	v_lshl_add_u64 v[142:143], v[200:201], 0, s[98:99]
	global_load_dwordx4 v[140:143], v[142:143], off
	v_lshl_add_u64 v[146:147], v[202:203], 0, s[98:99]
	global_load_dwordx4 v[144:147], v[146:147], off
	v_lshl_add_u64 v[150:151], v[204:205], 0, s[98:99]
	global_load_dwordx4 v[148:151], v[150:151], off
	v_lshl_add_u64 v[154:155], v[206:207], 0, s[98:99]
	global_load_dwordx4 v[152:155], v[154:155], off
	v_lshl_add_u64 v[158:159], v[208:209], 0, s[98:99]
	global_load_dwordx4 v[156:159], v[158:159], off
	v_lshl_add_u64 v[162:163], v[210:211], 0, s[98:99]
	global_load_dwordx4 v[160:163], v[162:163], off
	v_lshl_add_u64 v[166:167], v[212:213], 0, s[98:99]
	global_load_dwordx4 v[164:167], v[166:167], off
	s_add_u32 s98, s98, 0x60000
	s_addc_u32 s99, s99, 0
	s_mov_b32 s100, 0
.Lada_loop_p0:
	v_lshl_add_u64 v[170:171], v[16:17], 0, s[98:99]
	global_load_dwordx4 v[168:171], v[170:171], off
	v_lshl_add_u64 v[174:175], v[200:201], 0, s[98:99]
	global_load_dwordx4 v[172:175], v[174:175], off
	v_lshl_add_u64 v[178:179], v[202:203], 0, s[98:99]
	global_load_dwordx4 v[176:179], v[178:179], off
	v_lshl_add_u64 v[182:183], v[204:205], 0, s[98:99]
	global_load_dwordx4 v[180:183], v[182:183], off
	v_lshl_add_u64 v[186:187], v[206:207], 0, s[98:99]
	global_load_dwordx4 v[184:187], v[186:187], off
	v_lshl_add_u64 v[190:191], v[208:209], 0, s[98:99]
	global_load_dwordx4 v[188:191], v[190:191], off
	v_lshl_add_u64 v[194:195], v[210:211], 0, s[98:99]
	global_load_dwordx4 v[192:195], v[194:195], off
	v_lshl_add_u64 v[198:199], v[212:213], 0, s[98:99]
	global_load_dwordx4 v[196:199], v[198:199], off
	s_add_u32 s98, s98, 0x60000
	s_addc_u32 s99, s99, 0
	v_mov_b32_e32 v1, s28
	s_add_i32 s28, s28, 32
	ds_read_b128 v[50:53], v1
	ds_read_b128 v[54:57], v1 offset:16
	ds_read_b128 v[58:61], v1 offset:512
	ds_read_b128 v[62:65], v1 offset:528
	ds_read_b128 v[66:69], v1 offset:1024
	ds_read_b128 v[70:73], v1 offset:1040
	s_waitcnt lgkmcnt(5)
	v_mov_b32_e32 v74, v53
	s_waitcnt lgkmcnt(3)
	v_mov_b32_e32 v76, v61
	v_mov_b32_e32 v80, v57
	s_waitcnt lgkmcnt(1)
	v_mov_b32_e32 v78, v69
	v_mov_b32_e32 v82, v65
	s_waitcnt lgkmcnt(0)
	v_mov_b32_e32 v84, v73
	s_waitcnt vmcnt(31)
	v_pk_fma_f32 v[4:5], v[20:21], v[50:51], v[4:5] op_sel_hi:[1,0,1]
	v_pk_fma_f32 v[2:3], v[18:19], v[50:51], v[2:3] op_sel_hi:[1,0,1]
	v_pk_fma_f32 v[12:13], v[20:21], v[58:59], v[12:13] op_sel_hi:[1,0,1]
	v_pk_fma_f32 v[10:11], v[18:19], v[58:59], v[10:11] op_sel_hi:[1,0,1]
	v_pk_fma_f32 v[8:9], v[20:21], v[66:67], v[8:9] op_sel_hi:[1,0,1]
	v_pk_fma_f32 v[6:7], v[18:19], v[66:67], v[6:7] op_sel_hi:[1,0,1]
	s_waitcnt vmcnt(30)
	v_pk_fma_f32 v[2:3], v[22:23], v[50:51], v[2:3] op_sel:[0,1,0]
	v_pk_fma_f32 v[4:5], v[24:25], v[50:51], v[4:5] op_sel:[0,1,0]
	v_pk_fma_f32 v[10:11], v[22:23], v[58:59], v[10:11] op_sel:[0,1,0]
	v_pk_fma_f32 v[12:13], v[24:25], v[58:59], v[12:13] op_sel:[0,1,0]
	v_pk_fma_f32 v[6:7], v[22:23], v[66:67], v[6:7] op_sel:[0,1,0]
	v_pk_fma_f32 v[8:9], v[24:25], v[66:67], v[8:9] op_sel:[0,1,0]
	s_waitcnt vmcnt(29)
	v_pk_fma_f32 v[4:5], v[28:29], v[52:53], v[4:5] op_sel_hi:[1,0,1]
	v_pk_fma_f32 v[2:3], v[26:27], v[52:53], v[2:3] op_sel_hi:[1,0,1]
	v_pk_fma_f32 v[12:13], v[28:29], v[60:61], v[12:13] op_sel_hi:[1,0,1]
	v_pk_fma_f32 v[10:11], v[26:27], v[60:61], v[10:11] op_sel_hi:[1,0,1]
	v_pk_fma_f32 v[8:9], v[28:29], v[68:69], v[8:9] op_sel_hi:[1,0,1]
	v_pk_fma_f32 v[6:7], v[26:27], v[68:69], v[6:7] op_sel_hi:[1,0,1]
	s_waitcnt vmcnt(28)
	v_pk_fma_f32 v[4:5], v[32:33], v[74:75], v[4:5] op_sel_hi:[1,0,1]
	v_pk_fma_f32 v[2:3], v[30:31], v[74:75], v[2:3] op_sel_hi:[1,0,1]
	v_pk_fma_f32 v[12:13], v[32:33], v[76:77], v[12:13] op_sel_hi:[1,0,1]
	v_pk_fma_f32 v[10:11], v[30:31], v[76:77], v[10:11] op_sel_hi:[1,0,1]
	v_pk_fma_f32 v[8:9], v[32:33], v[78:79], v[8:9] op_sel_hi:[1,0,1]
	v_pk_fma_f32 v[6:7], v[30:31], v[78:79], v[6:7] op_sel_hi:[1,0,1]
	s_waitcnt vmcnt(27)
	v_pk_fma_f32 v[4:5], v[36:37], v[54:55], v[4:5] op_sel_hi:[1,0,1]
	v_pk_fma_f32 v[2:3], v[34:35], v[54:55], v[2:3] op_sel_hi:[1,0,1]
	v_pk_fma_f32 v[12:13], v[36:37], v[62:63], v[12:13] op_sel_hi:[1,0,1]
	v_pk_fma_f32 v[10:11], v[34:35], v[62:63], v[10:11] op_sel_hi:[1,0,1]
	v_pk_fma_f32 v[8:9], v[36:37], v[70:71], v[8:9] op_sel_hi:[1,0,1]
	v_pk_fma_f32 v[6:7], v[34:35], v[70:71], v[6:7] op_sel_hi:[1,0,1]
	s_waitcnt vmcnt(26)
	v_pk_fma_f32 v[4:5], v[40:41], v[54:55], v[4:5] op_sel:[0,1,0]
	v_pk_fma_f32 v[2:3], v[38:39], v[54:55], v[2:3] op_sel:[0,1,0]
	v_pk_fma_f32 v[12:13], v[40:41], v[62:63], v[12:13] op_sel:[0,1,0]
	v_pk_fma_f32 v[10:11], v[38:39], v[62:63], v[10:11] op_sel:[0,1,0]
	v_pk_fma_f32 v[8:9], v[40:41], v[70:71], v[8:9] op_sel:[0,1,0]
	v_pk_fma_f32 v[6:7], v[38:39], v[70:71], v[6:7] op_sel:[0,1,0]
	s_waitcnt vmcnt(25)
	v_pk_fma_f32 v[4:5], v[44:45], v[56:57], v[4:5] op_sel_hi:[1,0,1]
	v_pk_fma_f32 v[2:3], v[42:43], v[56:57], v[2:3] op_sel_hi:[1,0,1]
	v_pk_fma_f32 v[12:13], v[44:45], v[64:65], v[12:13] op_sel_hi:[1,0,1]
	v_pk_fma_f32 v[10:11], v[42:43], v[64:65], v[10:11] op_sel_hi:[1,0,1]
	v_pk_fma_f32 v[8:9], v[44:45], v[72:73], v[8:9] op_sel_hi:[1,0,1]
	v_pk_fma_f32 v[6:7], v[42:43], v[72:73], v[6:7] op_sel_hi:[1,0,1]
	s_waitcnt vmcnt(24)
	v_pk_fma_f32 v[4:5], v[48:49], v[80:81], v[4:5] op_sel_hi:[1,0,1]
	v_pk_fma_f32 v[2:3], v[46:47], v[80:81], v[2:3] op_sel_hi:[1,0,1]
	v_pk_fma_f32 v[12:13], v[48:49], v[82:83], v[12:13] op_sel_hi:[1,0,1]
	v_pk_fma_f32 v[10:11], v[46:47], v[82:83], v[10:11] op_sel_hi:[1,0,1]
	v_pk_fma_f32 v[8:9], v[48:49], v[84:85], v[8:9] op_sel_hi:[1,0,1]
	v_pk_fma_f32 v[6:7], v[46:47], v[84:85], v[6:7] op_sel_hi:[1,0,1]
	v_lshl_add_u64 v[20:21], v[16:17], 0, s[98:99]
	global_load_dwordx4 v[18:21], v[20:21], off
	v_lshl_add_u64 v[24:25], v[200:201], 0, s[98:99]
	global_load_dwordx4 v[22:25], v[24:25], off
	v_lshl_add_u64 v[28:29], v[202:203], 0, s[98:99]
	global_load_dwordx4 v[26:29], v[28:29], off
	v_lshl_add_u64 v[32:33], v[204:205], 0, s[98:99]
	global_load_dwordx4 v[30:33], v[32:33], off
	v_lshl_add_u64 v[36:37], v[206:207], 0, s[98:99]
	global_load_dwordx4 v[34:37], v[36:37], off
	v_lshl_add_u64 v[40:41], v[208:209], 0, s[98:99]
	global_load_dwordx4 v[38:41], v[40:41], off
	v_lshl_add_u64 v[44:45], v[210:211], 0, s[98:99]
	global_load_dwordx4 v[42:45], v[44:45], off
	v_lshl_add_u64 v[48:49], v[212:213], 0, s[98:99]
	global_load_dwordx4 v[46:49], v[48:49], off
	s_add_u32 s98, s98, 0x60000
	s_addc_u32 s99, s99, 0
	v_mov_b32_e32 v1, s28
	s_add_i32 s28, s28, 32
	ds_read_b128 v[50:53], v1
	ds_read_b128 v[54:57], v1 offset:16
	ds_read_b128 v[58:61], v1 offset:512
	ds_read_b128 v[62:65], v1 offset:528
	ds_read_b128 v[66:69], v1 offset:1024
	ds_read_b128 v[70:73], v1 offset:1040
	s_waitcnt lgkmcnt(5)
	v_mov_b32_e32 v74, v53
	s_waitcnt lgkmcnt(3)
	v_mov_b32_e32 v76, v61
	v_mov_b32_e32 v80, v57
	s_waitcnt lgkmcnt(1)
	v_mov_b32_e32 v78, v69
	v_mov_b32_e32 v82, v65
	s_waitcnt lgkmcnt(0)
	v_mov_b32_e32 v84, v73
	s_waitcnt vmcnt(31)
	v_pk_fma_f32 v[4:5], v[106:107], v[50:51], v[4:5] op_sel_hi:[1,0,1]
	v_pk_fma_f32 v[2:3], v[104:105], v[50:51], v[2:3] op_sel_hi:[1,0,1]
	v_pk_fma_f32 v[12:13], v[106:107], v[58:59], v[12:13] op_sel_hi:[1,0,1]
	v_pk_fma_f32 v[10:11], v[104:105], v[58:59], v[10:11] op_sel_hi:[1,0,1]
	v_pk_fma_f32 v[8:9], v[106:107], v[66:67], v[8:9] op_sel_hi:[1,0,1]
	v_pk_fma_f32 v[6:7], v[104:105], v[66:67], v[6:7] op_sel_hi:[1,0,1]
	s_waitcnt vmcnt(30)
	v_pk_fma_f32 v[2:3], v[108:109], v[50:51], v[2:3] op_sel:[0,1,0]
	v_pk_fma_f32 v[4:5], v[110:111], v[50:51], v[4:5] op_sel:[0,1,0]
	v_pk_fma_f32 v[10:11], v[108:109], v[58:59], v[10:11] op_sel:[0,1,0]
	v_pk_fma_f32 v[12:13], v[110:111], v[58:59], v[12:13] op_sel:[0,1,0]
	v_pk_fma_f32 v[6:7], v[108:109], v[66:67], v[6:7] op_sel:[0,1,0]
	v_pk_fma_f32 v[8:9], v[110:111], v[66:67], v[8:9] op_sel:[0,1,0]
	s_waitcnt vmcnt(29)
	v_pk_fma_f32 v[4:5], v[114:115], v[52:53], v[4:5] op_sel_hi:[1,0,1]
	v_pk_fma_f32 v[2:3], v[112:113], v[52:53], v[2:3] op_sel_hi:[1,0,1]
	v_pk_fma_f32 v[12:13], v[114:115], v[60:61], v[12:13] op_sel_hi:[1,0,1]
	v_pk_fma_f32 v[10:11], v[112:113], v[60:61], v[10:11] op_sel_hi:[1,0,1]
	v_pk_fma_f32 v[8:9], v[114:115], v[68:69], v[8:9] op_sel_hi:[1,0,1]
	v_pk_fma_f32 v[6:7], v[112:113], v[68:69], v[6:7] op_sel_hi:[1,0,1]
	s_waitcnt vmcnt(28)
	v_pk_fma_f32 v[4:5], v[118:119], v[74:75], v[4:5] op_sel_hi:[1,0,1]
	v_pk_fma_f32 v[2:3], v[116:117], v[74:75], v[2:3] op_sel_hi:[1,0,1]
	v_pk_fma_f32 v[12:13], v[118:119], v[76:77], v[12:13] op_sel_hi:[1,0,1]
	v_pk_fma_f32 v[10:11], v[116:117], v[76:77], v[10:11] op_sel_hi:[1,0,1]
	v_pk_fma_f32 v[8:9], v[118:119], v[78:79], v[8:9] op_sel_hi:[1,0,1]
	v_pk_fma_f32 v[6:7], v[116:117], v[78:79], v[6:7] op_sel_hi:[1,0,1]
	s_waitcnt vmcnt(27)
	v_pk_fma_f32 v[4:5], v[122:123], v[54:55], v[4:5] op_sel_hi:[1,0,1]
	v_pk_fma_f32 v[2:3], v[120:121], v[54:55], v[2:3] op_sel_hi:[1,0,1]
	v_pk_fma_f32 v[12:13], v[122:123], v[62:63], v[12:13] op_sel_hi:[1,0,1]
	v_pk_fma_f32 v[10:11], v[120:121], v[62:63], v[10:11] op_sel_hi:[1,0,1]
	v_pk_fma_f32 v[8:9], v[122:123], v[70:71], v[8:9] op_sel_hi:[1,0,1]
	v_pk_fma_f32 v[6:7], v[120:121], v[70:71], v[6:7] op_sel_hi:[1,0,1]
	s_waitcnt vmcnt(26)
	v_pk_fma_f32 v[4:5], v[126:127], v[54:55], v[4:5] op_sel:[0,1,0]
	v_pk_fma_f32 v[2:3], v[124:125], v[54:55], v[2:3] op_sel:[0,1,0]
	v_pk_fma_f32 v[12:13], v[126:127], v[62:63], v[12:13] op_sel:[0,1,0]
	v_pk_fma_f32 v[10:11], v[124:125], v[62:63], v[10:11] op_sel:[0,1,0]
	v_pk_fma_f32 v[8:9], v[126:127], v[70:71], v[8:9] op_sel:[0,1,0]
	v_pk_fma_f32 v[6:7], v[124:125], v[70:71], v[6:7] op_sel:[0,1,0]
	s_waitcnt vmcnt(25)
	v_pk_fma_f32 v[4:5], v[130:131], v[56:57], v[4:5] op_sel_hi:[1,0,1]
	v_pk_fma_f32 v[2:3], v[128:129], v[56:57], v[2:3] op_sel_hi:[1,0,1]
	v_pk_fma_f32 v[12:13], v[130:131], v[64:65], v[12:13] op_sel_hi:[1,0,1]
	v_pk_fma_f32 v[10:11], v[128:129], v[64:65], v[10:11] op_sel_hi:[1,0,1]
	v_pk_fma_f32 v[8:9], v[130:131], v[72:73], v[8:9] op_sel_hi:[1,0,1]
	v_pk_fma_f32 v[6:7], v[128:129], v[72:73], v[6:7] op_sel_hi:[1,0,1]
	s_waitcnt vmcnt(24)
	v_pk_fma_f32 v[4:5], v[134:135], v[80:81], v[4:5] op_sel_hi:[1,0,1]
	v_pk_fma_f32 v[2:3], v[132:133], v[80:81], v[2:3] op_sel_hi:[1,0,1]
	v_pk_fma_f32 v[12:13], v[134:135], v[82:83], v[12:13] op_sel_hi:[1,0,1]
	v_pk_fma_f32 v[10:11], v[132:133], v[82:83], v[10:11] op_sel_hi:[1,0,1]
	v_pk_fma_f32 v[8:9], v[134:135], v[84:85], v[8:9] op_sel_hi:[1,0,1]
	v_pk_fma_f32 v[6:7], v[132:133], v[84:85], v[6:7] op_sel_hi:[1,0,1]
	v_lshl_add_u64 v[106:107], v[16:17], 0, s[98:99]
	global_load_dwordx4 v[104:107], v[106:107], off
	v_lshl_add_u64 v[110:111], v[200:201], 0, s[98:99]
	global_load_dwordx4 v[108:111], v[110:111], off
	v_lshl_add_u64 v[114:115], v[202:203], 0, s[98:99]
	global_load_dwordx4 v[112:115], v[114:115], off
	v_lshl_add_u64 v[118:119], v[204:205], 0, s[98:99]
	global_load_dwordx4 v[116:119], v[118:119], off
	v_lshl_add_u64 v[122:123], v[206:207], 0, s[98:99]
	global_load_dwordx4 v[120:123], v[122:123], off
	v_lshl_add_u64 v[126:127], v[208:209], 0, s[98:99]
	global_load_dwordx4 v[124:127], v[126:127], off
	v_lshl_add_u64 v[130:131], v[210:211], 0, s[98:99]
	global_load_dwordx4 v[128:131], v[130:131], off
	v_lshl_add_u64 v[134:135], v[212:213], 0, s[98:99]
	global_load_dwordx4 v[132:135], v[134:135], off
	s_add_u32 s98, s98, 0x60000
	s_addc_u32 s99, s99, 0
	v_mov_b32_e32 v1, s28
	s_add_i32 s28, s28, 32
	ds_read_b128 v[50:53], v1
	ds_read_b128 v[54:57], v1 offset:16
	ds_read_b128 v[58:61], v1 offset:512
	ds_read_b128 v[62:65], v1 offset:528
	ds_read_b128 v[66:69], v1 offset:1024
	ds_read_b128 v[70:73], v1 offset:1040
	s_waitcnt lgkmcnt(5)
	v_mov_b32_e32 v74, v53
	s_waitcnt lgkmcnt(3)
	v_mov_b32_e32 v76, v61
	v_mov_b32_e32 v80, v57
	s_waitcnt lgkmcnt(1)
	v_mov_b32_e32 v78, v69
	v_mov_b32_e32 v82, v65
	s_waitcnt lgkmcnt(0)
	v_mov_b32_e32 v84, v73
	s_waitcnt vmcnt(31)
	v_pk_fma_f32 v[4:5], v[138:139], v[50:51], v[4:5] op_sel_hi:[1,0,1]
	v_pk_fma_f32 v[2:3], v[136:137], v[50:51], v[2:3] op_sel_hi:[1,0,1]
	v_pk_fma_f32 v[12:13], v[138:139], v[58:59], v[12:13] op_sel_hi:[1,0,1]
	v_pk_fma_f32 v[10:11], v[136:137], v[58:59], v[10:11] op_sel_hi:[1,0,1]
	v_pk_fma_f32 v[8:9], v[138:139], v[66:67], v[8:9] op_sel_hi:[1,0,1]
	v_pk_fma_f32 v[6:7], v[136:137], v[66:67], v[6:7] op_sel_hi:[1,0,1]
	s_waitcnt vmcnt(30)
	v_pk_fma_f32 v[2:3], v[140:141], v[50:51], v[2:3] op_sel:[0,1,0]
	v_pk_fma_f32 v[4:5], v[142:143], v[50:51], v[4:5] op_sel:[0,1,0]
	v_pk_fma_f32 v[10:11], v[140:141], v[58:59], v[10:11] op_sel:[0,1,0]
	v_pk_fma_f32 v[12:13], v[142:143], v[58:59], v[12:13] op_sel:[0,1,0]
	v_pk_fma_f32 v[6:7], v[140:141], v[66:67], v[6:7] op_sel:[0,1,0]
	v_pk_fma_f32 v[8:9], v[142:143], v[66:67], v[8:9] op_sel:[0,1,0]
	s_waitcnt vmcnt(29)
	v_pk_fma_f32 v[4:5], v[146:147], v[52:53], v[4:5] op_sel_hi:[1,0,1]
	v_pk_fma_f32 v[2:3], v[144:145], v[52:53], v[2:3] op_sel_hi:[1,0,1]
	v_pk_fma_f32 v[12:13], v[146:147], v[60:61], v[12:13] op_sel_hi:[1,0,1]
	v_pk_fma_f32 v[10:11], v[144:145], v[60:61], v[10:11] op_sel_hi:[1,0,1]
	v_pk_fma_f32 v[8:9], v[146:147], v[68:69], v[8:9] op_sel_hi:[1,0,1]
	v_pk_fma_f32 v[6:7], v[144:145], v[68:69], v[6:7] op_sel_hi:[1,0,1]
	s_waitcnt vmcnt(28)
	v_pk_fma_f32 v[4:5], v[150:151], v[74:75], v[4:5] op_sel_hi:[1,0,1]
	v_pk_fma_f32 v[2:3], v[148:149], v[74:75], v[2:3] op_sel_hi:[1,0,1]
	v_pk_fma_f32 v[12:13], v[150:151], v[76:77], v[12:13] op_sel_hi:[1,0,1]
	v_pk_fma_f32 v[10:11], v[148:149], v[76:77], v[10:11] op_sel_hi:[1,0,1]
	v_pk_fma_f32 v[8:9], v[150:151], v[78:79], v[8:9] op_sel_hi:[1,0,1]
	v_pk_fma_f32 v[6:7], v[148:149], v[78:79], v[6:7] op_sel_hi:[1,0,1]
	s_waitcnt vmcnt(27)
	v_pk_fma_f32 v[4:5], v[154:155], v[54:55], v[4:5] op_sel_hi:[1,0,1]
	v_pk_fma_f32 v[2:3], v[152:153], v[54:55], v[2:3] op_sel_hi:[1,0,1]
	v_pk_fma_f32 v[12:13], v[154:155], v[62:63], v[12:13] op_sel_hi:[1,0,1]
	v_pk_fma_f32 v[10:11], v[152:153], v[62:63], v[10:11] op_sel_hi:[1,0,1]
	v_pk_fma_f32 v[8:9], v[154:155], v[70:71], v[8:9] op_sel_hi:[1,0,1]
	v_pk_fma_f32 v[6:7], v[152:153], v[70:71], v[6:7] op_sel_hi:[1,0,1]
	s_waitcnt vmcnt(26)
	v_pk_fma_f32 v[4:5], v[158:159], v[54:55], v[4:5] op_sel:[0,1,0]
	v_pk_fma_f32 v[2:3], v[156:157], v[54:55], v[2:3] op_sel:[0,1,0]
	v_pk_fma_f32 v[12:13], v[158:159], v[62:63], v[12:13] op_sel:[0,1,0]
	v_pk_fma_f32 v[10:11], v[156:157], v[62:63], v[10:11] op_sel:[0,1,0]
	v_pk_fma_f32 v[8:9], v[158:159], v[70:71], v[8:9] op_sel:[0,1,0]
	v_pk_fma_f32 v[6:7], v[156:157], v[70:71], v[6:7] op_sel:[0,1,0]
	s_waitcnt vmcnt(25)
	v_pk_fma_f32 v[4:5], v[162:163], v[56:57], v[4:5] op_sel_hi:[1,0,1]
	v_pk_fma_f32 v[2:3], v[160:161], v[56:57], v[2:3] op_sel_hi:[1,0,1]
	v_pk_fma_f32 v[12:13], v[162:163], v[64:65], v[12:13] op_sel_hi:[1,0,1]
	v_pk_fma_f32 v[10:11], v[160:161], v[64:65], v[10:11] op_sel_hi:[1,0,1]
	v_pk_fma_f32 v[8:9], v[162:163], v[72:73], v[8:9] op_sel_hi:[1,0,1]
	v_pk_fma_f32 v[6:7], v[160:161], v[72:73], v[6:7] op_sel_hi:[1,0,1]
	s_waitcnt vmcnt(24)
	v_pk_fma_f32 v[4:5], v[166:167], v[80:81], v[4:5] op_sel_hi:[1,0,1]
	v_pk_fma_f32 v[2:3], v[164:165], v[80:81], v[2:3] op_sel_hi:[1,0,1]
	v_pk_fma_f32 v[12:13], v[166:167], v[82:83], v[12:13] op_sel_hi:[1,0,1]
	v_pk_fma_f32 v[10:11], v[164:165], v[82:83], v[10:11] op_sel_hi:[1,0,1]
	v_pk_fma_f32 v[8:9], v[166:167], v[84:85], v[8:9] op_sel_hi:[1,0,1]
	v_pk_fma_f32 v[6:7], v[164:165], v[84:85], v[6:7] op_sel_hi:[1,0,1]
	v_lshl_add_u64 v[138:139], v[16:17], 0, s[98:99]
	global_load_dwordx4 v[136:139], v[138:139], off
	v_lshl_add_u64 v[142:143], v[200:201], 0, s[98:99]
	global_load_dwordx4 v[140:143], v[142:143], off
	v_lshl_add_u64 v[146:147], v[202:203], 0, s[98:99]
	global_load_dwordx4 v[144:147], v[146:147], off
	v_lshl_add_u64 v[150:151], v[204:205], 0, s[98:99]
	global_load_dwordx4 v[148:151], v[150:151], off
	v_lshl_add_u64 v[154:155], v[206:207], 0, s[98:99]
	global_load_dwordx4 v[152:155], v[154:155], off
	v_lshl_add_u64 v[158:159], v[208:209], 0, s[98:99]
	global_load_dwordx4 v[156:159], v[158:159], off
	v_lshl_add_u64 v[162:163], v[210:211], 0, s[98:99]
	global_load_dwordx4 v[160:163], v[162:163], off
	v_lshl_add_u64 v[166:167], v[212:213], 0, s[98:99]
	global_load_dwordx4 v[164:167], v[166:167], off
	s_add_u32 s98, s98, 0x60000
	s_addc_u32 s99, s99, 0
	v_mov_b32_e32 v1, s28
	s_add_i32 s28, s28, 32
	ds_read_b128 v[50:53], v1
	ds_read_b128 v[54:57], v1 offset:16
	ds_read_b128 v[58:61], v1 offset:512
	ds_read_b128 v[62:65], v1 offset:528
	ds_read_b128 v[66:69], v1 offset:1024
	ds_read_b128 v[70:73], v1 offset:1040
	s_waitcnt lgkmcnt(5)
	v_mov_b32_e32 v74, v53
	s_waitcnt lgkmcnt(3)
	v_mov_b32_e32 v76, v61
	v_mov_b32_e32 v80, v57
	s_waitcnt lgkmcnt(1)
	v_mov_b32_e32 v78, v69
	v_mov_b32_e32 v82, v65
	s_waitcnt lgkmcnt(0)
	v_mov_b32_e32 v84, v73
	s_waitcnt vmcnt(31)
	v_pk_fma_f32 v[4:5], v[170:171], v[50:51], v[4:5] op_sel_hi:[1,0,1]
	v_pk_fma_f32 v[2:3], v[168:169], v[50:51], v[2:3] op_sel_hi:[1,0,1]
	v_pk_fma_f32 v[12:13], v[170:171], v[58:59], v[12:13] op_sel_hi:[1,0,1]
	v_pk_fma_f32 v[10:11], v[168:169], v[58:59], v[10:11] op_sel_hi:[1,0,1]
	v_pk_fma_f32 v[8:9], v[170:171], v[66:67], v[8:9] op_sel_hi:[1,0,1]
	v_pk_fma_f32 v[6:7], v[168:169], v[66:67], v[6:7] op_sel_hi:[1,0,1]
	s_waitcnt vmcnt(30)
	v_pk_fma_f32 v[2:3], v[172:173], v[50:51], v[2:3] op_sel:[0,1,0]
	v_pk_fma_f32 v[4:5], v[174:175], v[50:51], v[4:5] op_sel:[0,1,0]
	v_pk_fma_f32 v[10:11], v[172:173], v[58:59], v[10:11] op_sel:[0,1,0]
	v_pk_fma_f32 v[12:13], v[174:175], v[58:59], v[12:13] op_sel:[0,1,0]
	v_pk_fma_f32 v[6:7], v[172:173], v[66:67], v[6:7] op_sel:[0,1,0]
	v_pk_fma_f32 v[8:9], v[174:175], v[66:67], v[8:9] op_sel:[0,1,0]
	s_waitcnt vmcnt(29)
	v_pk_fma_f32 v[4:5], v[178:179], v[52:53], v[4:5] op_sel_hi:[1,0,1]
	v_pk_fma_f32 v[2:3], v[176:177], v[52:53], v[2:3] op_sel_hi:[1,0,1]
	v_pk_fma_f32 v[12:13], v[178:179], v[60:61], v[12:13] op_sel_hi:[1,0,1]
	v_pk_fma_f32 v[10:11], v[176:177], v[60:61], v[10:11] op_sel_hi:[1,0,1]
	v_pk_fma_f32 v[8:9], v[178:179], v[68:69], v[8:9] op_sel_hi:[1,0,1]
	v_pk_fma_f32 v[6:7], v[176:177], v[68:69], v[6:7] op_sel_hi:[1,0,1]
	s_waitcnt vmcnt(28)
	v_pk_fma_f32 v[4:5], v[182:183], v[74:75], v[4:5] op_sel_hi:[1,0,1]
	v_pk_fma_f32 v[2:3], v[180:181], v[74:75], v[2:3] op_sel_hi:[1,0,1]
	v_pk_fma_f32 v[12:13], v[182:183], v[76:77], v[12:13] op_sel_hi:[1,0,1]
	v_pk_fma_f32 v[10:11], v[180:181], v[76:77], v[10:11] op_sel_hi:[1,0,1]
	v_pk_fma_f32 v[8:9], v[182:183], v[78:79], v[8:9] op_sel_hi:[1,0,1]
	v_pk_fma_f32 v[6:7], v[180:181], v[78:79], v[6:7] op_sel_hi:[1,0,1]
	s_waitcnt vmcnt(27)
	v_pk_fma_f32 v[4:5], v[186:187], v[54:55], v[4:5] op_sel_hi:[1,0,1]
	v_pk_fma_f32 v[2:3], v[184:185], v[54:55], v[2:3] op_sel_hi:[1,0,1]
	v_pk_fma_f32 v[12:13], v[186:187], v[62:63], v[12:13] op_sel_hi:[1,0,1]
	v_pk_fma_f32 v[10:11], v[184:185], v[62:63], v[10:11] op_sel_hi:[1,0,1]
	v_pk_fma_f32 v[8:9], v[186:187], v[70:71], v[8:9] op_sel_hi:[1,0,1]
	v_pk_fma_f32 v[6:7], v[184:185], v[70:71], v[6:7] op_sel_hi:[1,0,1]
	s_waitcnt vmcnt(26)
	v_pk_fma_f32 v[4:5], v[190:191], v[54:55], v[4:5] op_sel:[0,1,0]
	v_pk_fma_f32 v[2:3], v[188:189], v[54:55], v[2:3] op_sel:[0,1,0]
	v_pk_fma_f32 v[12:13], v[190:191], v[62:63], v[12:13] op_sel:[0,1,0]
	v_pk_fma_f32 v[10:11], v[188:189], v[62:63], v[10:11] op_sel:[0,1,0]
	v_pk_fma_f32 v[8:9], v[190:191], v[70:71], v[8:9] op_sel:[0,1,0]
	v_pk_fma_f32 v[6:7], v[188:189], v[70:71], v[6:7] op_sel:[0,1,0]
	s_waitcnt vmcnt(25)
	v_pk_fma_f32 v[4:5], v[194:195], v[56:57], v[4:5] op_sel_hi:[1,0,1]
	v_pk_fma_f32 v[2:3], v[192:193], v[56:57], v[2:3] op_sel_hi:[1,0,1]
	v_pk_fma_f32 v[12:13], v[194:195], v[64:65], v[12:13] op_sel_hi:[1,0,1]
	v_pk_fma_f32 v[10:11], v[192:193], v[64:65], v[10:11] op_sel_hi:[1,0,1]
	v_pk_fma_f32 v[8:9], v[194:195], v[72:73], v[8:9] op_sel_hi:[1,0,1]
	v_pk_fma_f32 v[6:7], v[192:193], v[72:73], v[6:7] op_sel_hi:[1,0,1]
	s_waitcnt vmcnt(24)
	v_pk_fma_f32 v[4:5], v[198:199], v[80:81], v[4:5] op_sel_hi:[1,0,1]
	v_pk_fma_f32 v[2:3], v[196:197], v[80:81], v[2:3] op_sel_hi:[1,0,1]
	v_pk_fma_f32 v[12:13], v[198:199], v[82:83], v[12:13] op_sel_hi:[1,0,1]
	v_pk_fma_f32 v[10:11], v[196:197], v[82:83], v[10:11] op_sel_hi:[1,0,1]
	v_pk_fma_f32 v[8:9], v[198:199], v[84:85], v[8:9] op_sel_hi:[1,0,1]
	v_pk_fma_f32 v[6:7], v[196:197], v[84:85], v[6:7] op_sel_hi:[1,0,1]
	s_add_i32 s100, s100, 1
	s_cmp_lg_u32 s100, 3
	s_cbranch_scc1 .Lada_loop_p0
	v_lshl_add_u64 v[170:171], v[16:17], 0, s[98:99]
	global_load_dwordx4 v[168:171], v[170:171], off
	v_lshl_add_u64 v[174:175], v[200:201], 0, s[98:99]
	global_load_dwordx4 v[172:175], v[174:175], off
	v_lshl_add_u64 v[178:179], v[202:203], 0, s[98:99]
	global_load_dwordx4 v[176:179], v[178:179], off
	v_lshl_add_u64 v[182:183], v[204:205], 0, s[98:99]
	global_load_dwordx4 v[180:183], v[182:183], off
	v_lshl_add_u64 v[186:187], v[206:207], 0, s[98:99]
	global_load_dwordx4 v[184:187], v[186:187], off
	v_lshl_add_u64 v[190:191], v[208:209], 0, s[98:99]
	global_load_dwordx4 v[188:191], v[190:191], off
	v_lshl_add_u64 v[194:195], v[210:211], 0, s[98:99]
	global_load_dwordx4 v[192:195], v[194:195], off
	v_lshl_add_u64 v[198:199], v[212:213], 0, s[98:99]
	global_load_dwordx4 v[196:199], v[198:199], off
	s_add_u32 s98, s98, 0x60000
	s_addc_u32 s99, s99, 0
	v_mov_b32_e32 v1, s28
	s_add_i32 s28, s28, 32
	ds_read_b128 v[50:53], v1
	ds_read_b128 v[54:57], v1 offset:16
	ds_read_b128 v[58:61], v1 offset:512
	ds_read_b128 v[62:65], v1 offset:528
	ds_read_b128 v[66:69], v1 offset:1024
	ds_read_b128 v[70:73], v1 offset:1040
	s_waitcnt lgkmcnt(5)
	v_mov_b32_e32 v74, v53
	s_waitcnt lgkmcnt(3)
	v_mov_b32_e32 v76, v61
	v_mov_b32_e32 v80, v57
	s_waitcnt lgkmcnt(1)
	v_mov_b32_e32 v78, v69
	v_mov_b32_e32 v82, v65
	s_waitcnt lgkmcnt(0)
	v_mov_b32_e32 v84, v73
	s_waitcnt vmcnt(31)
	v_pk_fma_f32 v[4:5], v[20:21], v[50:51], v[4:5] op_sel_hi:[1,0,1]
	v_pk_fma_f32 v[2:3], v[18:19], v[50:51], v[2:3] op_sel_hi:[1,0,1]
	v_pk_fma_f32 v[12:13], v[20:21], v[58:59], v[12:13] op_sel_hi:[1,0,1]
	v_pk_fma_f32 v[10:11], v[18:19], v[58:59], v[10:11] op_sel_hi:[1,0,1]
	v_pk_fma_f32 v[8:9], v[20:21], v[66:67], v[8:9] op_sel_hi:[1,0,1]
	v_pk_fma_f32 v[6:7], v[18:19], v[66:67], v[6:7] op_sel_hi:[1,0,1]
	s_waitcnt vmcnt(30)
	v_pk_fma_f32 v[2:3], v[22:23], v[50:51], v[2:3] op_sel:[0,1,0]
	v_pk_fma_f32 v[4:5], v[24:25], v[50:51], v[4:5] op_sel:[0,1,0]
	v_pk_fma_f32 v[10:11], v[22:23], v[58:59], v[10:11] op_sel:[0,1,0]
	v_pk_fma_f32 v[12:13], v[24:25], v[58:59], v[12:13] op_sel:[0,1,0]
	v_pk_fma_f32 v[6:7], v[22:23], v[66:67], v[6:7] op_sel:[0,1,0]
	v_pk_fma_f32 v[8:9], v[24:25], v[66:67], v[8:9] op_sel:[0,1,0]
	s_waitcnt vmcnt(29)
	v_pk_fma_f32 v[4:5], v[28:29], v[52:53], v[4:5] op_sel_hi:[1,0,1]
	v_pk_fma_f32 v[2:3], v[26:27], v[52:53], v[2:3] op_sel_hi:[1,0,1]
	v_pk_fma_f32 v[12:13], v[28:29], v[60:61], v[12:13] op_sel_hi:[1,0,1]
	v_pk_fma_f32 v[10:11], v[26:27], v[60:61], v[10:11] op_sel_hi:[1,0,1]
	v_pk_fma_f32 v[8:9], v[28:29], v[68:69], v[8:9] op_sel_hi:[1,0,1]
	v_pk_fma_f32 v[6:7], v[26:27], v[68:69], v[6:7] op_sel_hi:[1,0,1]
	s_waitcnt vmcnt(28)
	v_pk_fma_f32 v[4:5], v[32:33], v[74:75], v[4:5] op_sel_hi:[1,0,1]
	v_pk_fma_f32 v[2:3], v[30:31], v[74:75], v[2:3] op_sel_hi:[1,0,1]
	v_pk_fma_f32 v[12:13], v[32:33], v[76:77], v[12:13] op_sel_hi:[1,0,1]
	v_pk_fma_f32 v[10:11], v[30:31], v[76:77], v[10:11] op_sel_hi:[1,0,1]
	v_pk_fma_f32 v[8:9], v[32:33], v[78:79], v[8:9] op_sel_hi:[1,0,1]
	v_pk_fma_f32 v[6:7], v[30:31], v[78:79], v[6:7] op_sel_hi:[1,0,1]
	s_waitcnt vmcnt(27)
	v_pk_fma_f32 v[4:5], v[36:37], v[54:55], v[4:5] op_sel_hi:[1,0,1]
	v_pk_fma_f32 v[2:3], v[34:35], v[54:55], v[2:3] op_sel_hi:[1,0,1]
	v_pk_fma_f32 v[12:13], v[36:37], v[62:63], v[12:13] op_sel_hi:[1,0,1]
	v_pk_fma_f32 v[10:11], v[34:35], v[62:63], v[10:11] op_sel_hi:[1,0,1]
	v_pk_fma_f32 v[8:9], v[36:37], v[70:71], v[8:9] op_sel_hi:[1,0,1]
	v_pk_fma_f32 v[6:7], v[34:35], v[70:71], v[6:7] op_sel_hi:[1,0,1]
	s_waitcnt vmcnt(26)
	v_pk_fma_f32 v[4:5], v[40:41], v[54:55], v[4:5] op_sel:[0,1,0]
	v_pk_fma_f32 v[2:3], v[38:39], v[54:55], v[2:3] op_sel:[0,1,0]
	v_pk_fma_f32 v[12:13], v[40:41], v[62:63], v[12:13] op_sel:[0,1,0]
	v_pk_fma_f32 v[10:11], v[38:39], v[62:63], v[10:11] op_sel:[0,1,0]
	v_pk_fma_f32 v[8:9], v[40:41], v[70:71], v[8:9] op_sel:[0,1,0]
	v_pk_fma_f32 v[6:7], v[38:39], v[70:71], v[6:7] op_sel:[0,1,0]
	s_waitcnt vmcnt(25)
	v_pk_fma_f32 v[4:5], v[44:45], v[56:57], v[4:5] op_sel_hi:[1,0,1]
	v_pk_fma_f32 v[2:3], v[42:43], v[56:57], v[2:3] op_sel_hi:[1,0,1]
	v_pk_fma_f32 v[12:13], v[44:45], v[64:65], v[12:13] op_sel_hi:[1,0,1]
	v_pk_fma_f32 v[10:11], v[42:43], v[64:65], v[10:11] op_sel_hi:[1,0,1]
	v_pk_fma_f32 v[8:9], v[44:45], v[72:73], v[8:9] op_sel_hi:[1,0,1]
	v_pk_fma_f32 v[6:7], v[42:43], v[72:73], v[6:7] op_sel_hi:[1,0,1]
	s_waitcnt vmcnt(24)
	v_pk_fma_f32 v[4:5], v[48:49], v[80:81], v[4:5] op_sel_hi:[1,0,1]
	v_pk_fma_f32 v[2:3], v[46:47], v[80:81], v[2:3] op_sel_hi:[1,0,1]
	v_pk_fma_f32 v[12:13], v[48:49], v[82:83], v[12:13] op_sel_hi:[1,0,1]
	v_pk_fma_f32 v[10:11], v[46:47], v[82:83], v[10:11] op_sel_hi:[1,0,1]
	v_pk_fma_f32 v[8:9], v[48:49], v[84:85], v[8:9] op_sel_hi:[1,0,1]
	v_pk_fma_f32 v[6:7], v[46:47], v[84:85], v[6:7] op_sel_hi:[1,0,1]
	v_mov_b32_e32 v1, s28
	s_add_i32 s28, s28, 32
	ds_read_b128 v[50:53], v1
	ds_read_b128 v[54:57], v1 offset:16
	ds_read_b128 v[58:61], v1 offset:512
	ds_read_b128 v[62:65], v1 offset:528
	ds_read_b128 v[66:69], v1 offset:1024
	ds_read_b128 v[70:73], v1 offset:1040
	s_waitcnt lgkmcnt(5)
	v_mov_b32_e32 v74, v53
	s_waitcnt lgkmcnt(3)
	v_mov_b32_e32 v76, v61
	v_mov_b32_e32 v80, v57
	s_waitcnt lgkmcnt(1)
	v_mov_b32_e32 v78, v69
	v_mov_b32_e32 v82, v65
	s_waitcnt lgkmcnt(0)
	v_mov_b32_e32 v84, v73
	s_waitcnt vmcnt(23)
	v_pk_fma_f32 v[4:5], v[106:107], v[50:51], v[4:5] op_sel_hi:[1,0,1]
	v_pk_fma_f32 v[2:3], v[104:105], v[50:51], v[2:3] op_sel_hi:[1,0,1]
	v_pk_fma_f32 v[12:13], v[106:107], v[58:59], v[12:13] op_sel_hi:[1,0,1]
	v_pk_fma_f32 v[10:11], v[104:105], v[58:59], v[10:11] op_sel_hi:[1,0,1]
	v_pk_fma_f32 v[8:9], v[106:107], v[66:67], v[8:9] op_sel_hi:[1,0,1]
	v_pk_fma_f32 v[6:7], v[104:105], v[66:67], v[6:7] op_sel_hi:[1,0,1]
	s_waitcnt vmcnt(22)
	v_pk_fma_f32 v[2:3], v[108:109], v[50:51], v[2:3] op_sel:[0,1,0]
	v_pk_fma_f32 v[4:5], v[110:111], v[50:51], v[4:5] op_sel:[0,1,0]
	v_pk_fma_f32 v[10:11], v[108:109], v[58:59], v[10:11] op_sel:[0,1,0]
	v_pk_fma_f32 v[12:13], v[110:111], v[58:59], v[12:13] op_sel:[0,1,0]
	v_pk_fma_f32 v[6:7], v[108:109], v[66:67], v[6:7] op_sel:[0,1,0]
	v_pk_fma_f32 v[8:9], v[110:111], v[66:67], v[8:9] op_sel:[0,1,0]
	s_waitcnt vmcnt(21)
	v_pk_fma_f32 v[4:5], v[114:115], v[52:53], v[4:5] op_sel_hi:[1,0,1]
	v_pk_fma_f32 v[2:3], v[112:113], v[52:53], v[2:3] op_sel_hi:[1,0,1]
	v_pk_fma_f32 v[12:13], v[114:115], v[60:61], v[12:13] op_sel_hi:[1,0,1]
	v_pk_fma_f32 v[10:11], v[112:113], v[60:61], v[10:11] op_sel_hi:[1,0,1]
	v_pk_fma_f32 v[8:9], v[114:115], v[68:69], v[8:9] op_sel_hi:[1,0,1]
	v_pk_fma_f32 v[6:7], v[112:113], v[68:69], v[6:7] op_sel_hi:[1,0,1]
	s_waitcnt vmcnt(20)
	v_pk_fma_f32 v[4:5], v[118:119], v[74:75], v[4:5] op_sel_hi:[1,0,1]
	v_pk_fma_f32 v[2:3], v[116:117], v[74:75], v[2:3] op_sel_hi:[1,0,1]
	v_pk_fma_f32 v[12:13], v[118:119], v[76:77], v[12:13] op_sel_hi:[1,0,1]
	v_pk_fma_f32 v[10:11], v[116:117], v[76:77], v[10:11] op_sel_hi:[1,0,1]
	v_pk_fma_f32 v[8:9], v[118:119], v[78:79], v[8:9] op_sel_hi:[1,0,1]
	v_pk_fma_f32 v[6:7], v[116:117], v[78:79], v[6:7] op_sel_hi:[1,0,1]
	s_waitcnt vmcnt(19)
	v_pk_fma_f32 v[4:5], v[122:123], v[54:55], v[4:5] op_sel_hi:[1,0,1]
	v_pk_fma_f32 v[2:3], v[120:121], v[54:55], v[2:3] op_sel_hi:[1,0,1]
	v_pk_fma_f32 v[12:13], v[122:123], v[62:63], v[12:13] op_sel_hi:[1,0,1]
	v_pk_fma_f32 v[10:11], v[120:121], v[62:63], v[10:11] op_sel_hi:[1,0,1]
	v_pk_fma_f32 v[8:9], v[122:123], v[70:71], v[8:9] op_sel_hi:[1,0,1]
	v_pk_fma_f32 v[6:7], v[120:121], v[70:71], v[6:7] op_sel_hi:[1,0,1]
	s_waitcnt vmcnt(18)
	v_pk_fma_f32 v[4:5], v[126:127], v[54:55], v[4:5] op_sel:[0,1,0]
	v_pk_fma_f32 v[2:3], v[124:125], v[54:55], v[2:3] op_sel:[0,1,0]
	v_pk_fma_f32 v[12:13], v[126:127], v[62:63], v[12:13] op_sel:[0,1,0]
	v_pk_fma_f32 v[10:11], v[124:125], v[62:63], v[10:11] op_sel:[0,1,0]
	v_pk_fma_f32 v[8:9], v[126:127], v[70:71], v[8:9] op_sel:[0,1,0]
	v_pk_fma_f32 v[6:7], v[124:125], v[70:71], v[6:7] op_sel:[0,1,0]
	s_waitcnt vmcnt(17)
	v_pk_fma_f32 v[4:5], v[130:131], v[56:57], v[4:5] op_sel_hi:[1,0,1]
	v_pk_fma_f32 v[2:3], v[128:129], v[56:57], v[2:3] op_sel_hi:[1,0,1]
	v_pk_fma_f32 v[12:13], v[130:131], v[64:65], v[12:13] op_sel_hi:[1,0,1]
	v_pk_fma_f32 v[10:11], v[128:129], v[64:65], v[10:11] op_sel_hi:[1,0,1]
	v_pk_fma_f32 v[8:9], v[130:131], v[72:73], v[8:9] op_sel_hi:[1,0,1]
	v_pk_fma_f32 v[6:7], v[128:129], v[72:73], v[6:7] op_sel_hi:[1,0,1]
	s_waitcnt vmcnt(16)
	v_pk_fma_f32 v[4:5], v[134:135], v[80:81], v[4:5] op_sel_hi:[1,0,1]
	v_pk_fma_f32 v[2:3], v[132:133], v[80:81], v[2:3] op_sel_hi:[1,0,1]
	v_pk_fma_f32 v[12:13], v[134:135], v[82:83], v[12:13] op_sel_hi:[1,0,1]
	v_pk_fma_f32 v[10:11], v[132:133], v[82:83], v[10:11] op_sel_hi:[1,0,1]
	v_pk_fma_f32 v[8:9], v[134:135], v[84:85], v[8:9] op_sel_hi:[1,0,1]
	v_pk_fma_f32 v[6:7], v[132:133], v[84:85], v[6:7] op_sel_hi:[1,0,1]
	v_mov_b32_e32 v1, s28
	s_add_i32 s28, s28, 32
	ds_read_b128 v[50:53], v1
	ds_read_b128 v[54:57], v1 offset:16
	ds_read_b128 v[58:61], v1 offset:512
	ds_read_b128 v[62:65], v1 offset:528
	ds_read_b128 v[66:69], v1 offset:1024
	ds_read_b128 v[70:73], v1 offset:1040
	s_waitcnt lgkmcnt(5)
	v_mov_b32_e32 v74, v53
	s_waitcnt lgkmcnt(3)
	v_mov_b32_e32 v76, v61
	v_mov_b32_e32 v80, v57
	s_waitcnt lgkmcnt(1)
	v_mov_b32_e32 v78, v69
	v_mov_b32_e32 v82, v65
	s_waitcnt lgkmcnt(0)
	v_mov_b32_e32 v84, v73
	s_waitcnt vmcnt(15)
	v_pk_fma_f32 v[4:5], v[138:139], v[50:51], v[4:5] op_sel_hi:[1,0,1]
	v_pk_fma_f32 v[2:3], v[136:137], v[50:51], v[2:3] op_sel_hi:[1,0,1]
	v_pk_fma_f32 v[12:13], v[138:139], v[58:59], v[12:13] op_sel_hi:[1,0,1]
	v_pk_fma_f32 v[10:11], v[136:137], v[58:59], v[10:11] op_sel_hi:[1,0,1]
	v_pk_fma_f32 v[8:9], v[138:139], v[66:67], v[8:9] op_sel_hi:[1,0,1]
	v_pk_fma_f32 v[6:7], v[136:137], v[66:67], v[6:7] op_sel_hi:[1,0,1]
	s_waitcnt vmcnt(14)
	v_pk_fma_f32 v[2:3], v[140:141], v[50:51], v[2:3] op_sel:[0,1,0]
	v_pk_fma_f32 v[4:5], v[142:143], v[50:51], v[4:5] op_sel:[0,1,0]
	v_pk_fma_f32 v[10:11], v[140:141], v[58:59], v[10:11] op_sel:[0,1,0]
	v_pk_fma_f32 v[12:13], v[142:143], v[58:59], v[12:13] op_sel:[0,1,0]
	v_pk_fma_f32 v[6:7], v[140:141], v[66:67], v[6:7] op_sel:[0,1,0]
	v_pk_fma_f32 v[8:9], v[142:143], v[66:67], v[8:9] op_sel:[0,1,0]
	s_waitcnt vmcnt(13)
	v_pk_fma_f32 v[4:5], v[146:147], v[52:53], v[4:5] op_sel_hi:[1,0,1]
	v_pk_fma_f32 v[2:3], v[144:145], v[52:53], v[2:3] op_sel_hi:[1,0,1]
	v_pk_fma_f32 v[12:13], v[146:147], v[60:61], v[12:13] op_sel_hi:[1,0,1]
	v_pk_fma_f32 v[10:11], v[144:145], v[60:61], v[10:11] op_sel_hi:[1,0,1]
	v_pk_fma_f32 v[8:9], v[146:147], v[68:69], v[8:9] op_sel_hi:[1,0,1]
	v_pk_fma_f32 v[6:7], v[144:145], v[68:69], v[6:7] op_sel_hi:[1,0,1]
	s_waitcnt vmcnt(12)
	v_pk_fma_f32 v[4:5], v[150:151], v[74:75], v[4:5] op_sel_hi:[1,0,1]
	v_pk_fma_f32 v[2:3], v[148:149], v[74:75], v[2:3] op_sel_hi:[1,0,1]
	v_pk_fma_f32 v[12:13], v[150:151], v[76:77], v[12:13] op_sel_hi:[1,0,1]
	v_pk_fma_f32 v[10:11], v[148:149], v[76:77], v[10:11] op_sel_hi:[1,0,1]
	v_pk_fma_f32 v[8:9], v[150:151], v[78:79], v[8:9] op_sel_hi:[1,0,1]
	v_pk_fma_f32 v[6:7], v[148:149], v[78:79], v[6:7] op_sel_hi:[1,0,1]
	s_waitcnt vmcnt(11)
	v_pk_fma_f32 v[4:5], v[154:155], v[54:55], v[4:5] op_sel_hi:[1,0,1]
	v_pk_fma_f32 v[2:3], v[152:153], v[54:55], v[2:3] op_sel_hi:[1,0,1]
	v_pk_fma_f32 v[12:13], v[154:155], v[62:63], v[12:13] op_sel_hi:[1,0,1]
	v_pk_fma_f32 v[10:11], v[152:153], v[62:63], v[10:11] op_sel_hi:[1,0,1]
	v_pk_fma_f32 v[8:9], v[154:155], v[70:71], v[8:9] op_sel_hi:[1,0,1]
	v_pk_fma_f32 v[6:7], v[152:153], v[70:71], v[6:7] op_sel_hi:[1,0,1]
	s_waitcnt vmcnt(10)
	v_pk_fma_f32 v[4:5], v[158:159], v[54:55], v[4:5] op_sel:[0,1,0]
	v_pk_fma_f32 v[2:3], v[156:157], v[54:55], v[2:3] op_sel:[0,1,0]
	v_pk_fma_f32 v[12:13], v[158:159], v[62:63], v[12:13] op_sel:[0,1,0]
	v_pk_fma_f32 v[10:11], v[156:157], v[62:63], v[10:11] op_sel:[0,1,0]
	v_pk_fma_f32 v[8:9], v[158:159], v[70:71], v[8:9] op_sel:[0,1,0]
	v_pk_fma_f32 v[6:7], v[156:157], v[70:71], v[6:7] op_sel:[0,1,0]
	s_waitcnt vmcnt(9)
	v_pk_fma_f32 v[4:5], v[162:163], v[56:57], v[4:5] op_sel_hi:[1,0,1]
	v_pk_fma_f32 v[2:3], v[160:161], v[56:57], v[2:3] op_sel_hi:[1,0,1]
	v_pk_fma_f32 v[12:13], v[162:163], v[64:65], v[12:13] op_sel_hi:[1,0,1]
	v_pk_fma_f32 v[10:11], v[160:161], v[64:65], v[10:11] op_sel_hi:[1,0,1]
	v_pk_fma_f32 v[8:9], v[162:163], v[72:73], v[8:9] op_sel_hi:[1,0,1]
	v_pk_fma_f32 v[6:7], v[160:161], v[72:73], v[6:7] op_sel_hi:[1,0,1]
	s_waitcnt vmcnt(8)
	v_pk_fma_f32 v[4:5], v[166:167], v[80:81], v[4:5] op_sel_hi:[1,0,1]
	v_pk_fma_f32 v[2:3], v[164:165], v[80:81], v[2:3] op_sel_hi:[1,0,1]
	v_pk_fma_f32 v[12:13], v[166:167], v[82:83], v[12:13] op_sel_hi:[1,0,1]
	v_pk_fma_f32 v[10:11], v[164:165], v[82:83], v[10:11] op_sel_hi:[1,0,1]
	v_pk_fma_f32 v[8:9], v[166:167], v[84:85], v[8:9] op_sel_hi:[1,0,1]
	v_pk_fma_f32 v[6:7], v[164:165], v[84:85], v[6:7] op_sel_hi:[1,0,1]
	v_mov_b32_e32 v1, s28
	s_add_i32 s28, s28, 32
	ds_read_b128 v[50:53], v1
	ds_read_b128 v[54:57], v1 offset:16
	ds_read_b128 v[58:61], v1 offset:512
	ds_read_b128 v[62:65], v1 offset:528
	ds_read_b128 v[66:69], v1 offset:1024
	ds_read_b128 v[70:73], v1 offset:1040
	s_waitcnt lgkmcnt(5)
	v_mov_b32_e32 v74, v53
	s_waitcnt lgkmcnt(3)
	v_mov_b32_e32 v76, v61
	v_mov_b32_e32 v80, v57
	s_waitcnt lgkmcnt(1)
	v_mov_b32_e32 v78, v69
	v_mov_b32_e32 v82, v65
	s_waitcnt lgkmcnt(0)
	v_mov_b32_e32 v84, v73
	s_waitcnt vmcnt(7)
	v_pk_fma_f32 v[4:5], v[170:171], v[50:51], v[4:5] op_sel_hi:[1,0,1]
	v_pk_fma_f32 v[2:3], v[168:169], v[50:51], v[2:3] op_sel_hi:[1,0,1]
	v_pk_fma_f32 v[12:13], v[170:171], v[58:59], v[12:13] op_sel_hi:[1,0,1]
	v_pk_fma_f32 v[10:11], v[168:169], v[58:59], v[10:11] op_sel_hi:[1,0,1]
	v_pk_fma_f32 v[8:9], v[170:171], v[66:67], v[8:9] op_sel_hi:[1,0,1]
	v_pk_fma_f32 v[6:7], v[168:169], v[66:67], v[6:7] op_sel_hi:[1,0,1]
	s_waitcnt vmcnt(6)
	v_pk_fma_f32 v[2:3], v[172:173], v[50:51], v[2:3] op_sel:[0,1,0]
	v_pk_fma_f32 v[4:5], v[174:175], v[50:51], v[4:5] op_sel:[0,1,0]
	v_pk_fma_f32 v[10:11], v[172:173], v[58:59], v[10:11] op_sel:[0,1,0]
	v_pk_fma_f32 v[12:13], v[174:175], v[58:59], v[12:13] op_sel:[0,1,0]
	v_pk_fma_f32 v[6:7], v[172:173], v[66:67], v[6:7] op_sel:[0,1,0]
	v_pk_fma_f32 v[8:9], v[174:175], v[66:67], v[8:9] op_sel:[0,1,0]
	s_waitcnt vmcnt(5)
	v_pk_fma_f32 v[4:5], v[178:179], v[52:53], v[4:5] op_sel_hi:[1,0,1]
	v_pk_fma_f32 v[2:3], v[176:177], v[52:53], v[2:3] op_sel_hi:[1,0,1]
	v_pk_fma_f32 v[12:13], v[178:179], v[60:61], v[12:13] op_sel_hi:[1,0,1]
	v_pk_fma_f32 v[10:11], v[176:177], v[60:61], v[10:11] op_sel_hi:[1,0,1]
	v_pk_fma_f32 v[8:9], v[178:179], v[68:69], v[8:9] op_sel_hi:[1,0,1]
	v_pk_fma_f32 v[6:7], v[176:177], v[68:69], v[6:7] op_sel_hi:[1,0,1]
	s_waitcnt vmcnt(4)
	v_pk_fma_f32 v[4:5], v[182:183], v[74:75], v[4:5] op_sel_hi:[1,0,1]
	v_pk_fma_f32 v[2:3], v[180:181], v[74:75], v[2:3] op_sel_hi:[1,0,1]
	v_pk_fma_f32 v[12:13], v[182:183], v[76:77], v[12:13] op_sel_hi:[1,0,1]
	v_pk_fma_f32 v[10:11], v[180:181], v[76:77], v[10:11] op_sel_hi:[1,0,1]
	v_pk_fma_f32 v[8:9], v[182:183], v[78:79], v[8:9] op_sel_hi:[1,0,1]
	v_pk_fma_f32 v[6:7], v[180:181], v[78:79], v[6:7] op_sel_hi:[1,0,1]
	s_waitcnt vmcnt(3)
	v_pk_fma_f32 v[4:5], v[186:187], v[54:55], v[4:5] op_sel_hi:[1,0,1]
	v_pk_fma_f32 v[2:3], v[184:185], v[54:55], v[2:3] op_sel_hi:[1,0,1]
	v_pk_fma_f32 v[12:13], v[186:187], v[62:63], v[12:13] op_sel_hi:[1,0,1]
	v_pk_fma_f32 v[10:11], v[184:185], v[62:63], v[10:11] op_sel_hi:[1,0,1]
	v_pk_fma_f32 v[8:9], v[186:187], v[70:71], v[8:9] op_sel_hi:[1,0,1]
	v_pk_fma_f32 v[6:7], v[184:185], v[70:71], v[6:7] op_sel_hi:[1,0,1]
	s_waitcnt vmcnt(2)
	v_pk_fma_f32 v[4:5], v[190:191], v[54:55], v[4:5] op_sel:[0,1,0]
	v_pk_fma_f32 v[2:3], v[188:189], v[54:55], v[2:3] op_sel:[0,1,0]
	v_pk_fma_f32 v[12:13], v[190:191], v[62:63], v[12:13] op_sel:[0,1,0]
	v_pk_fma_f32 v[10:11], v[188:189], v[62:63], v[10:11] op_sel:[0,1,0]
	v_pk_fma_f32 v[8:9], v[190:191], v[70:71], v[8:9] op_sel:[0,1,0]
	v_pk_fma_f32 v[6:7], v[188:189], v[70:71], v[6:7] op_sel:[0,1,0]
	s_waitcnt vmcnt(1)
	v_pk_fma_f32 v[4:5], v[194:195], v[56:57], v[4:5] op_sel_hi:[1,0,1]
	v_pk_fma_f32 v[2:3], v[192:193], v[56:57], v[2:3] op_sel_hi:[1,0,1]
	v_pk_fma_f32 v[12:13], v[194:195], v[64:65], v[12:13] op_sel_hi:[1,0,1]
	v_pk_fma_f32 v[10:11], v[192:193], v[64:65], v[10:11] op_sel_hi:[1,0,1]
	v_pk_fma_f32 v[8:9], v[194:195], v[72:73], v[8:9] op_sel_hi:[1,0,1]
	v_pk_fma_f32 v[6:7], v[192:193], v[72:73], v[6:7] op_sel_hi:[1,0,1]
	s_waitcnt vmcnt(0)
	v_pk_fma_f32 v[4:5], v[198:199], v[80:81], v[4:5] op_sel_hi:[1,0,1]
	v_pk_fma_f32 v[2:3], v[196:197], v[80:81], v[2:3] op_sel_hi:[1,0,1]
	v_pk_fma_f32 v[12:13], v[198:199], v[82:83], v[12:13] op_sel_hi:[1,0,1]
	v_pk_fma_f32 v[10:11], v[196:197], v[82:83], v[10:11] op_sel_hi:[1,0,1]
	v_pk_fma_f32 v[8:9], v[198:199], v[84:85], v[8:9] op_sel_hi:[1,0,1]
	v_pk_fma_f32 v[6:7], v[196:197], v[84:85], v[6:7] op_sel_hi:[1,0,1]
	s_mov_b32 s4, 0x600000
	s_mov_b32 s5, 0
	s_lshl_b32 s4, s35, 5
	s_add_i32 s4, s4, s34
	s_mul_hi_i32 s5, s4, 0x24000
	s_mul_i32 s4, s4, 0x24000
	s_add_u32 s4, s66, s4
	s_addc_u32 s5, s65, s5
	s_add_u32 s0, s4, s0
	s_addc_u32 s1, s5, s1
	v_lshl_add_u64 v[14:15], v[14:15], 2, s[0:1]
	global_store_dwordx4 v[14:15], v[2:5], off
	s_add_i32 s27, s27, s24
	s_cmpk_gt_i32 s27, 0xbf
	v_add_co_u32_e32 v2, vcc, s18, v14
	s_nop 1
	v_addc_co_u32_e32 v3, vcc, 0, v15, vcc
	global_store_dwordx4 v[2:3], v[10:13], off
	v_add_co_u32_e32 v2, vcc, 0x18000, v14
	s_nop 1
	v_addc_co_u32_e32 v3, vcc, 0, v15, vcc
	global_store_dwordx4 v[2:3], v[6:9], off
	s_barrier
	s_cbranch_scc0 .LBB0_417

.LBB0_1106:
	v_mov_b32_e32 v214, s12
	v_mov_b32_e32 v215, 0
	v_lshl_add_u64 v[200:201], v[16:17], 0, v[214:215]
	v_mov_b32_e32 v214, s13
	v_mov_b32_e32 v215, 0
	v_lshl_add_u64 v[202:203], v[16:17], 0, v[214:215]
	v_mov_b32_e32 v214, s14
	v_mov_b32_e32 v215, 0
	v_lshl_add_u64 v[204:205], v[16:17], 0, v[214:215]
	v_mov_b32_e32 v214, s15
	v_mov_b32_e32 v215, 0
	v_lshl_add_u64 v[206:207], v[16:17], 0, v[214:215]
	v_mov_b32_e32 v214, s16
	v_mov_b32_e32 v215, 0
	v_lshl_add_u64 v[208:209], v[16:17], 0, v[214:215]
	v_mov_b32_e32 v214, s17
	v_mov_b32_e32 v215, 0
	v_lshl_add_u64 v[210:211], v[16:17], 0, v[214:215]
	v_mov_b32_e32 v214, s18
	v_mov_b32_e32 v215, 0
	v_lshl_add_u64 v[212:213], v[16:17], 0, v[214:215]
	s_mov_b64 s[98:99], 0
	v_lshl_add_u64 v[20:21], v[16:17], 0, s[98:99]
	global_load_dwordx4 v[18:21], v[20:21], off
	v_lshl_add_u64 v[24:25], v[200:201], 0, s[98:99]
	global_load_dwordx4 v[22:25], v[24:25], off
	v_lshl_add_u64 v[28:29], v[202:203], 0, s[98:99]
	global_load_dwordx4 v[26:29], v[28:29], off
	v_lshl_add_u64 v[32:33], v[204:205], 0, s[98:99]
	global_load_dwordx4 v[30:33], v[32:33], off
	v_lshl_add_u64 v[36:37], v[206:207], 0, s[98:99]
	global_load_dwordx4 v[34:37], v[36:37], off
	v_lshl_add_u64 v[40:41], v[208:209], 0, s[98:99]
	global_load_dwordx4 v[38:41], v[40:41], off
	v_lshl_add_u64 v[44:45], v[210:211], 0, s[98:99]
	global_load_dwordx4 v[42:45], v[44:45], off
	v_lshl_add_u64 v[48:49], v[212:213], 0, s[98:99]
	global_load_dwordx4 v[46:49], v[48:49], off
	s_add_u32 s98, s98, 0x60000
	s_addc_u32 s99, s99, 0
	v_lshl_add_u64 v[106:107], v[16:17], 0, s[98:99]
	global_load_dwordx4 v[104:107], v[106:107], off
	v_lshl_add_u64 v[110:111], v[200:201], 0, s[98:99]
	global_load_dwordx4 v[108:111], v[110:111], off
	v_lshl_add_u64 v[114:115], v[202:203], 0, s[98:99]
	global_load_dwordx4 v[112:115], v[114:115], off
	v_lshl_add_u64 v[118:119], v[204:205], 0, s[98:99]
	global_load_dwordx4 v[116:119], v[118:119], off
	v_lshl_add_u64 v[122:123], v[206:207], 0, s[98:99]
	global_load_dwordx4 v[120:123], v[122:123], off
	v_lshl_add_u64 v[126:127], v[208:209], 0, s[98:99]
	global_load_dwordx4 v[124:127], v[126:127], off
	v_lshl_add_u64 v[130:131], v[210:211], 0, s[98:99]
	global_load_dwordx4 v[128:131], v[130:131], off
	v_lshl_add_u64 v[134:135], v[212:213], 0, s[98:99]
	global_load_dwordx4 v[132:135], v[134:135], off
	s_add_u32 s98, s98, 0x60000
	s_addc_u32 s99, s99, 0
	v_lshl_add_u64 v[138:139], v[16:17], 0, s[98:99]
	global_load_dwordx4 v[136:139], v[138:139], off
	v_lshl_add_u64 v[142:143], v[200:201], 0, s[98:99]
	global_load_dwordx4 v[140:143], v[142:143], off
	v_lshl_add_u64 v[146:147], v[202:203], 0, s[98:99]
	global_load_dwordx4 v[144:147], v[146:147], off
	v_lshl_add_u64 v[150:151], v[204:205], 0, s[98:99]
	global_load_dwordx4 v[148:151], v[150:151], off
	v_lshl_add_u64 v[154:155], v[206:207], 0, s[98:99]
	global_load_dwordx4 v[152:155], v[154:155], off
	v_lshl_add_u64 v[158:159], v[208:209], 0, s[98:99]
	global_load_dwordx4 v[156:159], v[158:159], off
	v_lshl_add_u64 v[162:163], v[210:211], 0, s[98:99]
	global_load_dwordx4 v[160:163], v[162:163], off
	v_lshl_add_u64 v[166:167], v[212:213], 0, s[98:99]
	global_load_dwordx4 v[164:167], v[166:167], off
	s_add_u32 s98, s98, 0x60000
	s_addc_u32 s99, s99, 0
	s_mov_b32 s100, 0
.Lada_loop_t0:
	v_lshl_add_u64 v[170:171], v[16:17], 0, s[98:99]
	global_load_dwordx4 v[168:171], v[170:171], off
	v_lshl_add_u64 v[174:175], v[200:201], 0, s[98:99]
	global_load_dwordx4 v[172:175], v[174:175], off
	v_lshl_add_u64 v[178:179], v[202:203], 0, s[98:99]
	global_load_dwordx4 v[176:179], v[178:179], off
	v_lshl_add_u64 v[182:183], v[204:205], 0, s[98:99]
	global_load_dwordx4 v[180:183], v[182:183], off
	v_lshl_add_u64 v[186:187], v[206:207], 0, s[98:99]
	global_load_dwordx4 v[184:187], v[186:187], off
	v_lshl_add_u64 v[190:191], v[208:209], 0, s[98:99]
	global_load_dwordx4 v[188:191], v[190:191], off
	v_lshl_add_u64 v[194:195], v[210:211], 0, s[98:99]
	global_load_dwordx4 v[192:195], v[194:195], off
	v_lshl_add_u64 v[198:199], v[212:213], 0, s[98:99]
	global_load_dwordx4 v[196:199], v[198:199], off
	s_add_u32 s98, s98, 0x60000
	s_addc_u32 s99, s99, 0
	v_mov_b32_e32 v1, s22
	s_add_i32 s22, s22, 32
	ds_read_b128 v[50:53], v1
	ds_read_b128 v[54:57], v1 offset:16
	ds_read_b128 v[58:61], v1 offset:512
	ds_read_b128 v[62:65], v1 offset:528
	ds_read_b128 v[66:69], v1 offset:1024
	ds_read_b128 v[70:73], v1 offset:1040
	s_waitcnt lgkmcnt(5)
	v_mov_b32_e32 v74, v53
	s_waitcnt lgkmcnt(3)
	v_mov_b32_e32 v76, v61
	v_mov_b32_e32 v80, v57
	s_waitcnt lgkmcnt(1)
	v_mov_b32_e32 v78, v69
	v_mov_b32_e32 v82, v65
	s_waitcnt lgkmcnt(0)
	v_mov_b32_e32 v84, v73
	s_waitcnt vmcnt(31)
	v_pk_fma_f32 v[4:5], v[20:21], v[50:51], v[4:5] op_sel_hi:[1,0,1]
	v_pk_fma_f32 v[2:3], v[18:19], v[50:51], v[2:3] op_sel_hi:[1,0,1]
	v_pk_fma_f32 v[12:13], v[20:21], v[58:59], v[12:13] op_sel_hi:[1,0,1]
	v_pk_fma_f32 v[10:11], v[18:19], v[58:59], v[10:11] op_sel_hi:[1,0,1]
	v_pk_fma_f32 v[8:9], v[20:21], v[66:67], v[8:9] op_sel_hi:[1,0,1]
	v_pk_fma_f32 v[6:7], v[18:19], v[66:67], v[6:7] op_sel_hi:[1,0,1]
	s_waitcnt vmcnt(30)
	v_pk_fma_f32 v[2:3], v[22:23], v[50:51], v[2:3] op_sel:[0,1,0]
	v_pk_fma_f32 v[4:5], v[24:25], v[50:51], v[4:5] op_sel:[0,1,0]
	v_pk_fma_f32 v[10:11], v[22:23], v[58:59], v[10:11] op_sel:[0,1,0]
	v_pk_fma_f32 v[12:13], v[24:25], v[58:59], v[12:13] op_sel:[0,1,0]
	v_pk_fma_f32 v[6:7], v[22:23], v[66:67], v[6:7] op_sel:[0,1,0]
	v_pk_fma_f32 v[8:9], v[24:25], v[66:67], v[8:9] op_sel:[0,1,0]
	s_waitcnt vmcnt(29)
	v_pk_fma_f32 v[4:5], v[28:29], v[52:53], v[4:5] op_sel_hi:[1,0,1]
	v_pk_fma_f32 v[2:3], v[26:27], v[52:53], v[2:3] op_sel_hi:[1,0,1]
	v_pk_fma_f32 v[12:13], v[28:29], v[60:61], v[12:13] op_sel_hi:[1,0,1]
	v_pk_fma_f32 v[10:11], v[26:27], v[60:61], v[10:11] op_sel_hi:[1,0,1]
	v_pk_fma_f32 v[8:9], v[28:29], v[68:69], v[8:9] op_sel_hi:[1,0,1]
	v_pk_fma_f32 v[6:7], v[26:27], v[68:69], v[6:7] op_sel_hi:[1,0,1]
	s_waitcnt vmcnt(28)
	v_pk_fma_f32 v[4:5], v[32:33], v[74:75], v[4:5] op_sel_hi:[1,0,1]
	v_pk_fma_f32 v[2:3], v[30:31], v[74:75], v[2:3] op_sel_hi:[1,0,1]
	v_pk_fma_f32 v[12:13], v[32:33], v[76:77], v[12:13] op_sel_hi:[1,0,1]
	v_pk_fma_f32 v[10:11], v[30:31], v[76:77], v[10:11] op_sel_hi:[1,0,1]
	v_pk_fma_f32 v[8:9], v[32:33], v[78:79], v[8:9] op_sel_hi:[1,0,1]
	v_pk_fma_f32 v[6:7], v[30:31], v[78:79], v[6:7] op_sel_hi:[1,0,1]
	s_waitcnt vmcnt(27)
	v_pk_fma_f32 v[4:5], v[36:37], v[54:55], v[4:5] op_sel_hi:[1,0,1]
	v_pk_fma_f32 v[2:3], v[34:35], v[54:55], v[2:3] op_sel_hi:[1,0,1]
	v_pk_fma_f32 v[12:13], v[36:37], v[62:63], v[12:13] op_sel_hi:[1,0,1]
	v_pk_fma_f32 v[10:11], v[34:35], v[62:63], v[10:11] op_sel_hi:[1,0,1]
	v_pk_fma_f32 v[8:9], v[36:37], v[70:71], v[8:9] op_sel_hi:[1,0,1]
	v_pk_fma_f32 v[6:7], v[34:35], v[70:71], v[6:7] op_sel_hi:[1,0,1]
	s_waitcnt vmcnt(26)
	v_pk_fma_f32 v[4:5], v[40:41], v[54:55], v[4:5] op_sel:[0,1,0]
	v_pk_fma_f32 v[2:3], v[38:39], v[54:55], v[2:3] op_sel:[0,1,0]
	v_pk_fma_f32 v[12:13], v[40:41], v[62:63], v[12:13] op_sel:[0,1,0]
	v_pk_fma_f32 v[10:11], v[38:39], v[62:63], v[10:11] op_sel:[0,1,0]
	v_pk_fma_f32 v[8:9], v[40:41], v[70:71], v[8:9] op_sel:[0,1,0]
	v_pk_fma_f32 v[6:7], v[38:39], v[70:71], v[6:7] op_sel:[0,1,0]
	s_waitcnt vmcnt(25)
	v_pk_fma_f32 v[4:5], v[44:45], v[56:57], v[4:5] op_sel_hi:[1,0,1]
	v_pk_fma_f32 v[2:3], v[42:43], v[56:57], v[2:3] op_sel_hi:[1,0,1]
	v_pk_fma_f32 v[12:13], v[44:45], v[64:65], v[12:13] op_sel_hi:[1,0,1]
	v_pk_fma_f32 v[10:11], v[42:43], v[64:65], v[10:11] op_sel_hi:[1,0,1]
	v_pk_fma_f32 v[8:9], v[44:45], v[72:73], v[8:9] op_sel_hi:[1,0,1]
	v_pk_fma_f32 v[6:7], v[42:43], v[72:73], v[6:7] op_sel_hi:[1,0,1]
	s_waitcnt vmcnt(24)
	v_pk_fma_f32 v[4:5], v[48:49], v[80:81], v[4:5] op_sel_hi:[1,0,1]
	v_pk_fma_f32 v[2:3], v[46:47], v[80:81], v[2:3] op_sel_hi:[1,0,1]
	v_pk_fma_f32 v[12:13], v[48:49], v[82:83], v[12:13] op_sel_hi:[1,0,1]
	v_pk_fma_f32 v[10:11], v[46:47], v[82:83], v[10:11] op_sel_hi:[1,0,1]
	v_pk_fma_f32 v[8:9], v[48:49], v[84:85], v[8:9] op_sel_hi:[1,0,1]
	v_pk_fma_f32 v[6:7], v[46:47], v[84:85], v[6:7] op_sel_hi:[1,0,1]
	v_lshl_add_u64 v[20:21], v[16:17], 0, s[98:99]
	global_load_dwordx4 v[18:21], v[20:21], off
	v_lshl_add_u64 v[24:25], v[200:201], 0, s[98:99]
	global_load_dwordx4 v[22:25], v[24:25], off
	v_lshl_add_u64 v[28:29], v[202:203], 0, s[98:99]
	global_load_dwordx4 v[26:29], v[28:29], off
	v_lshl_add_u64 v[32:33], v[204:205], 0, s[98:99]
	global_load_dwordx4 v[30:33], v[32:33], off
	v_lshl_add_u64 v[36:37], v[206:207], 0, s[98:99]
	global_load_dwordx4 v[34:37], v[36:37], off
	v_lshl_add_u64 v[40:41], v[208:209], 0, s[98:99]
	global_load_dwordx4 v[38:41], v[40:41], off
	v_lshl_add_u64 v[44:45], v[210:211], 0, s[98:99]
	global_load_dwordx4 v[42:45], v[44:45], off
	v_lshl_add_u64 v[48:49], v[212:213], 0, s[98:99]
	global_load_dwordx4 v[46:49], v[48:49], off
	s_add_u32 s98, s98, 0x60000
	s_addc_u32 s99, s99, 0
	v_mov_b32_e32 v1, s22
	s_add_i32 s22, s22, 32
	ds_read_b128 v[50:53], v1
	ds_read_b128 v[54:57], v1 offset:16
	ds_read_b128 v[58:61], v1 offset:512
	ds_read_b128 v[62:65], v1 offset:528
	ds_read_b128 v[66:69], v1 offset:1024
	ds_read_b128 v[70:73], v1 offset:1040
	s_waitcnt lgkmcnt(5)
	v_mov_b32_e32 v74, v53
	s_waitcnt lgkmcnt(3)
	v_mov_b32_e32 v76, v61
	v_mov_b32_e32 v80, v57
	s_waitcnt lgkmcnt(1)
	v_mov_b32_e32 v78, v69
	v_mov_b32_e32 v82, v65
	s_waitcnt lgkmcnt(0)
	v_mov_b32_e32 v84, v73
	s_waitcnt vmcnt(31)
	v_pk_fma_f32 v[4:5], v[106:107], v[50:51], v[4:5] op_sel_hi:[1,0,1]
	v_pk_fma_f32 v[2:3], v[104:105], v[50:51], v[2:3] op_sel_hi:[1,0,1]
	v_pk_fma_f32 v[12:13], v[106:107], v[58:59], v[12:13] op_sel_hi:[1,0,1]
	v_pk_fma_f32 v[10:11], v[104:105], v[58:59], v[10:11] op_sel_hi:[1,0,1]
	v_pk_fma_f32 v[8:9], v[106:107], v[66:67], v[8:9] op_sel_hi:[1,0,1]
	v_pk_fma_f32 v[6:7], v[104:105], v[66:67], v[6:7] op_sel_hi:[1,0,1]
	s_waitcnt vmcnt(30)
	v_pk_fma_f32 v[2:3], v[108:109], v[50:51], v[2:3] op_sel:[0,1,0]
	v_pk_fma_f32 v[4:5], v[110:111], v[50:51], v[4:5] op_sel:[0,1,0]
	v_pk_fma_f32 v[10:11], v[108:109], v[58:59], v[10:11] op_sel:[0,1,0]
	v_pk_fma_f32 v[12:13], v[110:111], v[58:59], v[12:13] op_sel:[0,1,0]
	v_pk_fma_f32 v[6:7], v[108:109], v[66:67], v[6:7] op_sel:[0,1,0]
	v_pk_fma_f32 v[8:9], v[110:111], v[66:67], v[8:9] op_sel:[0,1,0]
	s_waitcnt vmcnt(29)
	v_pk_fma_f32 v[4:5], v[114:115], v[52:53], v[4:5] op_sel_hi:[1,0,1]
	v_pk_fma_f32 v[2:3], v[112:113], v[52:53], v[2:3] op_sel_hi:[1,0,1]
	v_pk_fma_f32 v[12:13], v[114:115], v[60:61], v[12:13] op_sel_hi:[1,0,1]
	v_pk_fma_f32 v[10:11], v[112:113], v[60:61], v[10:11] op_sel_hi:[1,0,1]
	v_pk_fma_f32 v[8:9], v[114:115], v[68:69], v[8:9] op_sel_hi:[1,0,1]
	v_pk_fma_f32 v[6:7], v[112:113], v[68:69], v[6:7] op_sel_hi:[1,0,1]
	s_waitcnt vmcnt(28)
	v_pk_fma_f32 v[4:5], v[118:119], v[74:75], v[4:5] op_sel_hi:[1,0,1]
	v_pk_fma_f32 v[2:3], v[116:117], v[74:75], v[2:3] op_sel_hi:[1,0,1]
	v_pk_fma_f32 v[12:13], v[118:119], v[76:77], v[12:13] op_sel_hi:[1,0,1]
	v_pk_fma_f32 v[10:11], v[116:117], v[76:77], v[10:11] op_sel_hi:[1,0,1]
	v_pk_fma_f32 v[8:9], v[118:119], v[78:79], v[8:9] op_sel_hi:[1,0,1]
	v_pk_fma_f32 v[6:7], v[116:117], v[78:79], v[6:7] op_sel_hi:[1,0,1]
	s_waitcnt vmcnt(27)
	v_pk_fma_f32 v[4:5], v[122:123], v[54:55], v[4:5] op_sel_hi:[1,0,1]
	v_pk_fma_f32 v[2:3], v[120:121], v[54:55], v[2:3] op_sel_hi:[1,0,1]
	v_pk_fma_f32 v[12:13], v[122:123], v[62:63], v[12:13] op_sel_hi:[1,0,1]
	v_pk_fma_f32 v[10:11], v[120:121], v[62:63], v[10:11] op_sel_hi:[1,0,1]
	v_pk_fma_f32 v[8:9], v[122:123], v[70:71], v[8:9] op_sel_hi:[1,0,1]
	v_pk_fma_f32 v[6:7], v[120:121], v[70:71], v[6:7] op_sel_hi:[1,0,1]
	s_waitcnt vmcnt(26)
	v_pk_fma_f32 v[4:5], v[126:127], v[54:55], v[4:5] op_sel:[0,1,0]
	v_pk_fma_f32 v[2:3], v[124:125], v[54:55], v[2:3] op_sel:[0,1,0]
	v_pk_fma_f32 v[12:13], v[126:127], v[62:63], v[12:13] op_sel:[0,1,0]
	v_pk_fma_f32 v[10:11], v[124:125], v[62:63], v[10:11] op_sel:[0,1,0]
	v_pk_fma_f32 v[8:9], v[126:127], v[70:71], v[8:9] op_sel:[0,1,0]
	v_pk_fma_f32 v[6:7], v[124:125], v[70:71], v[6:7] op_sel:[0,1,0]
	s_waitcnt vmcnt(25)
	v_pk_fma_f32 v[4:5], v[130:131], v[56:57], v[4:5] op_sel_hi:[1,0,1]
	v_pk_fma_f32 v[2:3], v[128:129], v[56:57], v[2:3] op_sel_hi:[1,0,1]
	v_pk_fma_f32 v[12:13], v[130:131], v[64:65], v[12:13] op_sel_hi:[1,0,1]
	v_pk_fma_f32 v[10:11], v[128:129], v[64:65], v[10:11] op_sel_hi:[1,0,1]
	v_pk_fma_f32 v[8:9], v[130:131], v[72:73], v[8:9] op_sel_hi:[1,0,1]
	v_pk_fma_f32 v[6:7], v[128:129], v[72:73], v[6:7] op_sel_hi:[1,0,1]
	s_waitcnt vmcnt(24)
	v_pk_fma_f32 v[4:5], v[134:135], v[80:81], v[4:5] op_sel_hi:[1,0,1]
	v_pk_fma_f32 v[2:3], v[132:133], v[80:81], v[2:3] op_sel_hi:[1,0,1]
	v_pk_fma_f32 v[12:13], v[134:135], v[82:83], v[12:13] op_sel_hi:[1,0,1]
	v_pk_fma_f32 v[10:11], v[132:133], v[82:83], v[10:11] op_sel_hi:[1,0,1]
	v_pk_fma_f32 v[8:9], v[134:135], v[84:85], v[8:9] op_sel_hi:[1,0,1]
	v_pk_fma_f32 v[6:7], v[132:133], v[84:85], v[6:7] op_sel_hi:[1,0,1]
	v_lshl_add_u64 v[106:107], v[16:17], 0, s[98:99]
	global_load_dwordx4 v[104:107], v[106:107], off
	v_lshl_add_u64 v[110:111], v[200:201], 0, s[98:99]
	global_load_dwordx4 v[108:111], v[110:111], off
	v_lshl_add_u64 v[114:115], v[202:203], 0, s[98:99]
	global_load_dwordx4 v[112:115], v[114:115], off
	v_lshl_add_u64 v[118:119], v[204:205], 0, s[98:99]
	global_load_dwordx4 v[116:119], v[118:119], off
	v_lshl_add_u64 v[122:123], v[206:207], 0, s[98:99]
	global_load_dwordx4 v[120:123], v[122:123], off
	v_lshl_add_u64 v[126:127], v[208:209], 0, s[98:99]
	global_load_dwordx4 v[124:127], v[126:127], off
	v_lshl_add_u64 v[130:131], v[210:211], 0, s[98:99]
	global_load_dwordx4 v[128:131], v[130:131], off
	v_lshl_add_u64 v[134:135], v[212:213], 0, s[98:99]
	global_load_dwordx4 v[132:135], v[134:135], off
	s_add_u32 s98, s98, 0x60000
	s_addc_u32 s99, s99, 0
	v_mov_b32_e32 v1, s22
	s_add_i32 s22, s22, 32
	ds_read_b128 v[50:53], v1
	ds_read_b128 v[54:57], v1 offset:16
	ds_read_b128 v[58:61], v1 offset:512
	ds_read_b128 v[62:65], v1 offset:528
	ds_read_b128 v[66:69], v1 offset:1024
	ds_read_b128 v[70:73], v1 offset:1040
	s_waitcnt lgkmcnt(5)
	v_mov_b32_e32 v74, v53
	s_waitcnt lgkmcnt(3)
	v_mov_b32_e32 v76, v61
	v_mov_b32_e32 v80, v57
	s_waitcnt lgkmcnt(1)
	v_mov_b32_e32 v78, v69
	v_mov_b32_e32 v82, v65
	s_waitcnt lgkmcnt(0)
	v_mov_b32_e32 v84, v73
	s_waitcnt vmcnt(31)
	v_pk_fma_f32 v[4:5], v[138:139], v[50:51], v[4:5] op_sel_hi:[1,0,1]
	v_pk_fma_f32 v[2:3], v[136:137], v[50:51], v[2:3] op_sel_hi:[1,0,1]
	v_pk_fma_f32 v[12:13], v[138:139], v[58:59], v[12:13] op_sel_hi:[1,0,1]
	v_pk_fma_f32 v[10:11], v[136:137], v[58:59], v[10:11] op_sel_hi:[1,0,1]
	v_pk_fma_f32 v[8:9], v[138:139], v[66:67], v[8:9] op_sel_hi:[1,0,1]
	v_pk_fma_f32 v[6:7], v[136:137], v[66:67], v[6:7] op_sel_hi:[1,0,1]
	s_waitcnt vmcnt(30)
	v_pk_fma_f32 v[2:3], v[140:141], v[50:51], v[2:3] op_sel:[0,1,0]
	v_pk_fma_f32 v[4:5], v[142:143], v[50:51], v[4:5] op_sel:[0,1,0]
	v_pk_fma_f32 v[10:11], v[140:141], v[58:59], v[10:11] op_sel:[0,1,0]
	v_pk_fma_f32 v[12:13], v[142:143], v[58:59], v[12:13] op_sel:[0,1,0]
	v_pk_fma_f32 v[6:7], v[140:141], v[66:67], v[6:7] op_sel:[0,1,0]
	v_pk_fma_f32 v[8:9], v[142:143], v[66:67], v[8:9] op_sel:[0,1,0]
	s_waitcnt vmcnt(29)
	v_pk_fma_f32 v[4:5], v[146:147], v[52:53], v[4:5] op_sel_hi:[1,0,1]
	v_pk_fma_f32 v[2:3], v[144:145], v[52:53], v[2:3] op_sel_hi:[1,0,1]
	v_pk_fma_f32 v[12:13], v[146:147], v[60:61], v[12:13] op_sel_hi:[1,0,1]
	v_pk_fma_f32 v[10:11], v[144:145], v[60:61], v[10:11] op_sel_hi:[1,0,1]
	v_pk_fma_f32 v[8:9], v[146:147], v[68:69], v[8:9] op_sel_hi:[1,0,1]
	v_pk_fma_f32 v[6:7], v[144:145], v[68:69], v[6:7] op_sel_hi:[1,0,1]
	s_waitcnt vmcnt(28)
	v_pk_fma_f32 v[4:5], v[150:151], v[74:75], v[4:5] op_sel_hi:[1,0,1]
	v_pk_fma_f32 v[2:3], v[148:149], v[74:75], v[2:3] op_sel_hi:[1,0,1]
	v_pk_fma_f32 v[12:13], v[150:151], v[76:77], v[12:13] op_sel_hi:[1,0,1]
	v_pk_fma_f32 v[10:11], v[148:149], v[76:77], v[10:11] op_sel_hi:[1,0,1]
	v_pk_fma_f32 v[8:9], v[150:151], v[78:79], v[8:9] op_sel_hi:[1,0,1]
	v_pk_fma_f32 v[6:7], v[148:149], v[78:79], v[6:7] op_sel_hi:[1,0,1]
	s_waitcnt vmcnt(27)
	v_pk_fma_f32 v[4:5], v[154:155], v[54:55], v[4:5] op_sel_hi:[1,0,1]
	v_pk_fma_f32 v[2:3], v[152:153], v[54:55], v[2:3] op_sel_hi:[1,0,1]
	v_pk_fma_f32 v[12:13], v[154:155], v[62:63], v[12:13] op_sel_hi:[1,0,1]
	v_pk_fma_f32 v[10:11], v[152:153], v[62:63], v[10:11] op_sel_hi:[1,0,1]
	v_pk_fma_f32 v[8:9], v[154:155], v[70:71], v[8:9] op_sel_hi:[1,0,1]
	v_pk_fma_f32 v[6:7], v[152:153], v[70:71], v[6:7] op_sel_hi:[1,0,1]
	s_waitcnt vmcnt(26)
	v_pk_fma_f32 v[4:5], v[158:159], v[54:55], v[4:5] op_sel:[0,1,0]
	v_pk_fma_f32 v[2:3], v[156:157], v[54:55], v[2:3] op_sel:[0,1,0]
	v_pk_fma_f32 v[12:13], v[158:159], v[62:63], v[12:13] op_sel:[0,1,0]
	v_pk_fma_f32 v[10:11], v[156:157], v[62:63], v[10:11] op_sel:[0,1,0]
	v_pk_fma_f32 v[8:9], v[158:159], v[70:71], v[8:9] op_sel:[0,1,0]
	v_pk_fma_f32 v[6:7], v[156:157], v[70:71], v[6:7] op_sel:[0,1,0]
	s_waitcnt vmcnt(25)
	v_pk_fma_f32 v[4:5], v[162:163], v[56:57], v[4:5] op_sel_hi:[1,0,1]
	v_pk_fma_f32 v[2:3], v[160:161], v[56:57], v[2:3] op_sel_hi:[1,0,1]
	v_pk_fma_f32 v[12:13], v[162:163], v[64:65], v[12:13] op_sel_hi:[1,0,1]
	v_pk_fma_f32 v[10:11], v[160:161], v[64:65], v[10:11] op_sel_hi:[1,0,1]
	v_pk_fma_f32 v[8:9], v[162:163], v[72:73], v[8:9] op_sel_hi:[1,0,1]
	v_pk_fma_f32 v[6:7], v[160:161], v[72:73], v[6:7] op_sel_hi:[1,0,1]
	s_waitcnt vmcnt(24)
	v_pk_fma_f32 v[4:5], v[166:167], v[80:81], v[4:5] op_sel_hi:[1,0,1]
	v_pk_fma_f32 v[2:3], v[164:165], v[80:81], v[2:3] op_sel_hi:[1,0,1]
	v_pk_fma_f32 v[12:13], v[166:167], v[82:83], v[12:13] op_sel_hi:[1,0,1]
	v_pk_fma_f32 v[10:11], v[164:165], v[82:83], v[10:11] op_sel_hi:[1,0,1]
	v_pk_fma_f32 v[8:9], v[166:167], v[84:85], v[8:9] op_sel_hi:[1,0,1]
	v_pk_fma_f32 v[6:7], v[164:165], v[84:85], v[6:7] op_sel_hi:[1,0,1]
	v_lshl_add_u64 v[138:139], v[16:17], 0, s[98:99]
	global_load_dwordx4 v[136:139], v[138:139], off
	v_lshl_add_u64 v[142:143], v[200:201], 0, s[98:99]
	global_load_dwordx4 v[140:143], v[142:143], off
	v_lshl_add_u64 v[146:147], v[202:203], 0, s[98:99]
	global_load_dwordx4 v[144:147], v[146:147], off
	v_lshl_add_u64 v[150:151], v[204:205], 0, s[98:99]
	global_load_dwordx4 v[148:151], v[150:151], off
	v_lshl_add_u64 v[154:155], v[206:207], 0, s[98:99]
	global_load_dwordx4 v[152:155], v[154:155], off
	v_lshl_add_u64 v[158:159], v[208:209], 0, s[98:99]
	global_load_dwordx4 v[156:159], v[158:159], off
	v_lshl_add_u64 v[162:163], v[210:211], 0, s[98:99]
	global_load_dwordx4 v[160:163], v[162:163], off
	v_lshl_add_u64 v[166:167], v[212:213], 0, s[98:99]
	global_load_dwordx4 v[164:167], v[166:167], off
	s_add_u32 s98, s98, 0x60000
	s_addc_u32 s99, s99, 0
	v_mov_b32_e32 v1, s22
	s_add_i32 s22, s22, 32
	ds_read_b128 v[50:53], v1
	ds_read_b128 v[54:57], v1 offset:16
	ds_read_b128 v[58:61], v1 offset:512
	ds_read_b128 v[62:65], v1 offset:528
	ds_read_b128 v[66:69], v1 offset:1024
	ds_read_b128 v[70:73], v1 offset:1040
	s_waitcnt lgkmcnt(5)
	v_mov_b32_e32 v74, v53
	s_waitcnt lgkmcnt(3)
	v_mov_b32_e32 v76, v61
	v_mov_b32_e32 v80, v57
	s_waitcnt lgkmcnt(1)
	v_mov_b32_e32 v78, v69
	v_mov_b32_e32 v82, v65
	s_waitcnt lgkmcnt(0)
	v_mov_b32_e32 v84, v73
	s_waitcnt vmcnt(31)
	v_pk_fma_f32 v[4:5], v[170:171], v[50:51], v[4:5] op_sel_hi:[1,0,1]
	v_pk_fma_f32 v[2:3], v[168:169], v[50:51], v[2:3] op_sel_hi:[1,0,1]
	v_pk_fma_f32 v[12:13], v[170:171], v[58:59], v[12:13] op_sel_hi:[1,0,1]
	v_pk_fma_f32 v[10:11], v[168:169], v[58:59], v[10:11] op_sel_hi:[1,0,1]
	v_pk_fma_f32 v[8:9], v[170:171], v[66:67], v[8:9] op_sel_hi:[1,0,1]
	v_pk_fma_f32 v[6:7], v[168:169], v[66:67], v[6:7] op_sel_hi:[1,0,1]
	s_waitcnt vmcnt(30)
	v_pk_fma_f32 v[2:3], v[172:173], v[50:51], v[2:3] op_sel:[0,1,0]
	v_pk_fma_f32 v[4:5], v[174:175], v[50:51], v[4:5] op_sel:[0,1,0]
	v_pk_fma_f32 v[10:11], v[172:173], v[58:59], v[10:11] op_sel:[0,1,0]
	v_pk_fma_f32 v[12:13], v[174:175], v[58:59], v[12:13] op_sel:[0,1,0]
	v_pk_fma_f32 v[6:7], v[172:173], v[66:67], v[6:7] op_sel:[0,1,0]
	v_pk_fma_f32 v[8:9], v[174:175], v[66:67], v[8:9] op_sel:[0,1,0]
	s_waitcnt vmcnt(29)
	v_pk_fma_f32 v[4:5], v[178:179], v[52:53], v[4:5] op_sel_hi:[1,0,1]
	v_pk_fma_f32 v[2:3], v[176:177], v[52:53], v[2:3] op_sel_hi:[1,0,1]
	v_pk_fma_f32 v[12:13], v[178:179], v[60:61], v[12:13] op_sel_hi:[1,0,1]
	v_pk_fma_f32 v[10:11], v[176:177], v[60:61], v[10:11] op_sel_hi:[1,0,1]
	v_pk_fma_f32 v[8:9], v[178:179], v[68:69], v[8:9] op_sel_hi:[1,0,1]
	v_pk_fma_f32 v[6:7], v[176:177], v[68:69], v[6:7] op_sel_hi:[1,0,1]
	s_waitcnt vmcnt(28)
	v_pk_fma_f32 v[4:5], v[182:183], v[74:75], v[4:5] op_sel_hi:[1,0,1]
	v_pk_fma_f32 v[2:3], v[180:181], v[74:75], v[2:3] op_sel_hi:[1,0,1]
	v_pk_fma_f32 v[12:13], v[182:183], v[76:77], v[12:13] op_sel_hi:[1,0,1]
	v_pk_fma_f32 v[10:11], v[180:181], v[76:77], v[10:11] op_sel_hi:[1,0,1]
	v_pk_fma_f32 v[8:9], v[182:183], v[78:79], v[8:9] op_sel_hi:[1,0,1]
	v_pk_fma_f32 v[6:7], v[180:181], v[78:79], v[6:7] op_sel_hi:[1,0,1]
	s_waitcnt vmcnt(27)
	v_pk_fma_f32 v[4:5], v[186:187], v[54:55], v[4:5] op_sel_hi:[1,0,1]
	v_pk_fma_f32 v[2:3], v[184:185], v[54:55], v[2:3] op_sel_hi:[1,0,1]
	v_pk_fma_f32 v[12:13], v[186:187], v[62:63], v[12:13] op_sel_hi:[1,0,1]
	v_pk_fma_f32 v[10:11], v[184:185], v[62:63], v[10:11] op_sel_hi:[1,0,1]
	v_pk_fma_f32 v[8:9], v[186:187], v[70:71], v[8:9] op_sel_hi:[1,0,1]
	v_pk_fma_f32 v[6:7], v[184:185], v[70:71], v[6:7] op_sel_hi:[1,0,1]
	s_waitcnt vmcnt(26)
	v_pk_fma_f32 v[4:5], v[190:191], v[54:55], v[4:5] op_sel:[0,1,0]
	v_pk_fma_f32 v[2:3], v[188:189], v[54:55], v[2:3] op_sel:[0,1,0]
	v_pk_fma_f32 v[12:13], v[190:191], v[62:63], v[12:13] op_sel:[0,1,0]
	v_pk_fma_f32 v[10:11], v[188:189], v[62:63], v[10:11] op_sel:[0,1,0]
	v_pk_fma_f32 v[8:9], v[190:191], v[70:71], v[8:9] op_sel:[0,1,0]
	v_pk_fma_f32 v[6:7], v[188:189], v[70:71], v[6:7] op_sel:[0,1,0]
	s_waitcnt vmcnt(25)
	v_pk_fma_f32 v[4:5], v[194:195], v[56:57], v[4:5] op_sel_hi:[1,0,1]
	v_pk_fma_f32 v[2:3], v[192:193], v[56:57], v[2:3] op_sel_hi:[1,0,1]
	v_pk_fma_f32 v[12:13], v[194:195], v[64:65], v[12:13] op_sel_hi:[1,0,1]
	v_pk_fma_f32 v[10:11], v[192:193], v[64:65], v[10:11] op_sel_hi:[1,0,1]
	v_pk_fma_f32 v[8:9], v[194:195], v[72:73], v[8:9] op_sel_hi:[1,0,1]
	v_pk_fma_f32 v[6:7], v[192:193], v[72:73], v[6:7] op_sel_hi:[1,0,1]
	s_waitcnt vmcnt(24)
	v_pk_fma_f32 v[4:5], v[198:199], v[80:81], v[4:5] op_sel_hi:[1,0,1]
	v_pk_fma_f32 v[2:3], v[196:197], v[80:81], v[2:3] op_sel_hi:[1,0,1]
	v_pk_fma_f32 v[12:13], v[198:199], v[82:83], v[12:13] op_sel_hi:[1,0,1]
	v_pk_fma_f32 v[10:11], v[196:197], v[82:83], v[10:11] op_sel_hi:[1,0,1]
	v_pk_fma_f32 v[8:9], v[198:199], v[84:85], v[8:9] op_sel_hi:[1,0,1]
	v_pk_fma_f32 v[6:7], v[196:197], v[84:85], v[6:7] op_sel_hi:[1,0,1]
	s_add_i32 s100, s100, 1
	s_cmp_lg_u32 s100, 3
	s_cbranch_scc1 .Lada_loop_t0
	v_lshl_add_u64 v[170:171], v[16:17], 0, s[98:99]
	global_load_dwordx4 v[168:171], v[170:171], off
	v_lshl_add_u64 v[174:175], v[200:201], 0, s[98:99]
	global_load_dwordx4 v[172:175], v[174:175], off
	v_lshl_add_u64 v[178:179], v[202:203], 0, s[98:99]
	global_load_dwordx4 v[176:179], v[178:179], off
	v_lshl_add_u64 v[182:183], v[204:205], 0, s[98:99]
	global_load_dwordx4 v[180:183], v[182:183], off
	v_lshl_add_u64 v[186:187], v[206:207], 0, s[98:99]
	global_load_dwordx4 v[184:187], v[186:187], off
	v_lshl_add_u64 v[190:191], v[208:209], 0, s[98:99]
	global_load_dwordx4 v[188:191], v[190:191], off
	v_lshl_add_u64 v[194:195], v[210:211], 0, s[98:99]
	global_load_dwordx4 v[192:195], v[194:195], off
	v_lshl_add_u64 v[198:199], v[212:213], 0, s[98:99]
	global_load_dwordx4 v[196:199], v[198:199], off
	s_add_u32 s98, s98, 0x60000
	s_addc_u32 s99, s99, 0
	v_mov_b32_e32 v1, s22
	s_add_i32 s22, s22, 32
	ds_read_b128 v[50:53], v1
	ds_read_b128 v[54:57], v1 offset:16
	ds_read_b128 v[58:61], v1 offset:512
	ds_read_b128 v[62:65], v1 offset:528
	ds_read_b128 v[66:69], v1 offset:1024
	ds_read_b128 v[70:73], v1 offset:1040
	s_waitcnt lgkmcnt(5)
	v_mov_b32_e32 v74, v53
	s_waitcnt lgkmcnt(3)
	v_mov_b32_e32 v76, v61
	v_mov_b32_e32 v80, v57
	s_waitcnt lgkmcnt(1)
	v_mov_b32_e32 v78, v69
	v_mov_b32_e32 v82, v65
	s_waitcnt lgkmcnt(0)
	v_mov_b32_e32 v84, v73
	s_waitcnt vmcnt(31)
	v_pk_fma_f32 v[4:5], v[20:21], v[50:51], v[4:5] op_sel_hi:[1,0,1]
	v_pk_fma_f32 v[2:3], v[18:19], v[50:51], v[2:3] op_sel_hi:[1,0,1]
	v_pk_fma_f32 v[12:13], v[20:21], v[58:59], v[12:13] op_sel_hi:[1,0,1]
	v_pk_fma_f32 v[10:11], v[18:19], v[58:59], v[10:11] op_sel_hi:[1,0,1]
	v_pk_fma_f32 v[8:9], v[20:21], v[66:67], v[8:9] op_sel_hi:[1,0,1]
	v_pk_fma_f32 v[6:7], v[18:19], v[66:67], v[6:7] op_sel_hi:[1,0,1]
	s_waitcnt vmcnt(30)
	v_pk_fma_f32 v[2:3], v[22:23], v[50:51], v[2:3] op_sel:[0,1,0]
	v_pk_fma_f32 v[4:5], v[24:25], v[50:51], v[4:5] op_sel:[0,1,0]
	v_pk_fma_f32 v[10:11], v[22:23], v[58:59], v[10:11] op_sel:[0,1,0]
	v_pk_fma_f32 v[12:13], v[24:25], v[58:59], v[12:13] op_sel:[0,1,0]
	v_pk_fma_f32 v[6:7], v[22:23], v[66:67], v[6:7] op_sel:[0,1,0]
	v_pk_fma_f32 v[8:9], v[24:25], v[66:67], v[8:9] op_sel:[0,1,0]
	s_waitcnt vmcnt(29)
	v_pk_fma_f32 v[4:5], v[28:29], v[52:53], v[4:5] op_sel_hi:[1,0,1]
	v_pk_fma_f32 v[2:3], v[26:27], v[52:53], v[2:3] op_sel_hi:[1,0,1]
	v_pk_fma_f32 v[12:13], v[28:29], v[60:61], v[12:13] op_sel_hi:[1,0,1]
	v_pk_fma_f32 v[10:11], v[26:27], v[60:61], v[10:11] op_sel_hi:[1,0,1]
	v_pk_fma_f32 v[8:9], v[28:29], v[68:69], v[8:9] op_sel_hi:[1,0,1]
	v_pk_fma_f32 v[6:7], v[26:27], v[68:69], v[6:7] op_sel_hi:[1,0,1]
	s_waitcnt vmcnt(28)
	v_pk_fma_f32 v[4:5], v[32:33], v[74:75], v[4:5] op_sel_hi:[1,0,1]
	v_pk_fma_f32 v[2:3], v[30:31], v[74:75], v[2:3] op_sel_hi:[1,0,1]
	v_pk_fma_f32 v[12:13], v[32:33], v[76:77], v[12:13] op_sel_hi:[1,0,1]
	v_pk_fma_f32 v[10:11], v[30:31], v[76:77], v[10:11] op_sel_hi:[1,0,1]
	v_pk_fma_f32 v[8:9], v[32:33], v[78:79], v[8:9] op_sel_hi:[1,0,1]
	v_pk_fma_f32 v[6:7], v[30:31], v[78:79], v[6:7] op_sel_hi:[1,0,1]
	s_waitcnt vmcnt(27)
	v_pk_fma_f32 v[4:5], v[36:37], v[54:55], v[4:5] op_sel_hi:[1,0,1]
	v_pk_fma_f32 v[2:3], v[34:35], v[54:55], v[2:3] op_sel_hi:[1,0,1]
	v_pk_fma_f32 v[12:13], v[36:37], v[62:63], v[12:13] op_sel_hi:[1,0,1]
	v_pk_fma_f32 v[10:11], v[34:35], v[62:63], v[10:11] op_sel_hi:[1,0,1]
	v_pk_fma_f32 v[8:9], v[36:37], v[70:71], v[8:9] op_sel_hi:[1,0,1]
	v_pk_fma_f32 v[6:7], v[34:35], v[70:71], v[6:7] op_sel_hi:[1,0,1]
	s_waitcnt vmcnt(26)
	v_pk_fma_f32 v[4:5], v[40:41], v[54:55], v[4:5] op_sel:[0,1,0]
	v_pk_fma_f32 v[2:3], v[38:39], v[54:55], v[2:3] op_sel:[0,1,0]
	v_pk_fma_f32 v[12:13], v[40:41], v[62:63], v[12:13] op_sel:[0,1,0]
	v_pk_fma_f32 v[10:11], v[38:39], v[62:63], v[10:11] op_sel:[0,1,0]
	v_pk_fma_f32 v[8:9], v[40:41], v[70:71], v[8:9] op_sel:[0,1,0]
	v_pk_fma_f32 v[6:7], v[38:39], v[70:71], v[6:7] op_sel:[0,1,0]
	s_waitcnt vmcnt(25)
	v_pk_fma_f32 v[4:5], v[44:45], v[56:57], v[4:5] op_sel_hi:[1,0,1]
	v_pk_fma_f32 v[2:3], v[42:43], v[56:57], v[2:3] op_sel_hi:[1,0,1]
	v_pk_fma_f32 v[12:13], v[44:45], v[64:65], v[12:13] op_sel_hi:[1,0,1]
	v_pk_fma_f32 v[10:11], v[42:43], v[64:65], v[10:11] op_sel_hi:[1,0,1]
	v_pk_fma_f32 v[8:9], v[44:45], v[72:73], v[8:9] op_sel_hi:[1,0,1]
	v_pk_fma_f32 v[6:7], v[42:43], v[72:73], v[6:7] op_sel_hi:[1,0,1]
	s_waitcnt vmcnt(24)
	v_pk_fma_f32 v[4:5], v[48:49], v[80:81], v[4:5] op_sel_hi:[1,0,1]
	v_pk_fma_f32 v[2:3], v[46:47], v[80:81], v[2:3] op_sel_hi:[1,0,1]
	v_pk_fma_f32 v[12:13], v[48:49], v[82:83], v[12:13] op_sel_hi:[1,0,1]
	v_pk_fma_f32 v[10:11], v[46:47], v[82:83], v[10:11] op_sel_hi:[1,0,1]
	v_pk_fma_f32 v[8:9], v[48:49], v[84:85], v[8:9] op_sel_hi:[1,0,1]
	v_pk_fma_f32 v[6:7], v[46:47], v[84:85], v[6:7] op_sel_hi:[1,0,1]
	v_mov_b32_e32 v1, s22
	s_add_i32 s22, s22, 32
	ds_read_b128 v[50:53], v1
	ds_read_b128 v[54:57], v1 offset:16
	ds_read_b128 v[58:61], v1 offset:512
	ds_read_b128 v[62:65], v1 offset:528
	ds_read_b128 v[66:69], v1 offset:1024
	ds_read_b128 v[70:73], v1 offset:1040
	s_waitcnt lgkmcnt(5)
	v_mov_b32_e32 v74, v53
	s_waitcnt lgkmcnt(3)
	v_mov_b32_e32 v76, v61
	v_mov_b32_e32 v80, v57
	s_waitcnt lgkmcnt(1)
	v_mov_b32_e32 v78, v69
	v_mov_b32_e32 v82, v65
	s_waitcnt lgkmcnt(0)
	v_mov_b32_e32 v84, v73
	s_waitcnt vmcnt(23)
	v_pk_fma_f32 v[4:5], v[106:107], v[50:51], v[4:5] op_sel_hi:[1,0,1]
	v_pk_fma_f32 v[2:3], v[104:105], v[50:51], v[2:3] op_sel_hi:[1,0,1]
	v_pk_fma_f32 v[12:13], v[106:107], v[58:59], v[12:13] op_sel_hi:[1,0,1]
	v_pk_fma_f32 v[10:11], v[104:105], v[58:59], v[10:11] op_sel_hi:[1,0,1]
	v_pk_fma_f32 v[8:9], v[106:107], v[66:67], v[8:9] op_sel_hi:[1,0,1]
	v_pk_fma_f32 v[6:7], v[104:105], v[66:67], v[6:7] op_sel_hi:[1,0,1]
	s_waitcnt vmcnt(22)
	v_pk_fma_f32 v[2:3], v[108:109], v[50:51], v[2:3] op_sel:[0,1,0]
	v_pk_fma_f32 v[4:5], v[110:111], v[50:51], v[4:5] op_sel:[0,1,0]
	v_pk_fma_f32 v[10:11], v[108:109], v[58:59], v[10:11] op_sel:[0,1,0]
	v_pk_fma_f32 v[12:13], v[110:111], v[58:59], v[12:13] op_sel:[0,1,0]
	v_pk_fma_f32 v[6:7], v[108:109], v[66:67], v[6:7] op_sel:[0,1,0]
	v_pk_fma_f32 v[8:9], v[110:111], v[66:67], v[8:9] op_sel:[0,1,0]
	s_waitcnt vmcnt(21)
	v_pk_fma_f32 v[4:5], v[114:115], v[52:53], v[4:5] op_sel_hi:[1,0,1]
	v_pk_fma_f32 v[2:3], v[112:113], v[52:53], v[2:3] op_sel_hi:[1,0,1]
	v_pk_fma_f32 v[12:13], v[114:115], v[60:61], v[12:13] op_sel_hi:[1,0,1]
	v_pk_fma_f32 v[10:11], v[112:113], v[60:61], v[10:11] op_sel_hi:[1,0,1]
	v_pk_fma_f32 v[8:9], v[114:115], v[68:69], v[8:9] op_sel_hi:[1,0,1]
	v_pk_fma_f32 v[6:7], v[112:113], v[68:69], v[6:7] op_sel_hi:[1,0,1]
	s_waitcnt vmcnt(20)
	v_pk_fma_f32 v[4:5], v[118:119], v[74:75], v[4:5] op_sel_hi:[1,0,1]
	v_pk_fma_f32 v[2:3], v[116:117], v[74:75], v[2:3] op_sel_hi:[1,0,1]
	v_pk_fma_f32 v[12:13], v[118:119], v[76:77], v[12:13] op_sel_hi:[1,0,1]
	v_pk_fma_f32 v[10:11], v[116:117], v[76:77], v[10:11] op_sel_hi:[1,0,1]
	v_pk_fma_f32 v[8:9], v[118:119], v[78:79], v[8:9] op_sel_hi:[1,0,1]
	v_pk_fma_f32 v[6:7], v[116:117], v[78:79], v[6:7] op_sel_hi:[1,0,1]
	s_waitcnt vmcnt(19)
	v_pk_fma_f32 v[4:5], v[122:123], v[54:55], v[4:5] op_sel_hi:[1,0,1]
	v_pk_fma_f32 v[2:3], v[120:121], v[54:55], v[2:3] op_sel_hi:[1,0,1]
	v_pk_fma_f32 v[12:13], v[122:123], v[62:63], v[12:13] op_sel_hi:[1,0,1]
	v_pk_fma_f32 v[10:11], v[120:121], v[62:63], v[10:11] op_sel_hi:[1,0,1]
	v_pk_fma_f32 v[8:9], v[122:123], v[70:71], v[8:9] op_sel_hi:[1,0,1]
	v_pk_fma_f32 v[6:7], v[120:121], v[70:71], v[6:7] op_sel_hi:[1,0,1]
	s_waitcnt vmcnt(18)
	v_pk_fma_f32 v[4:5], v[126:127], v[54:55], v[4:5] op_sel:[0,1,0]
	v_pk_fma_f32 v[2:3], v[124:125], v[54:55], v[2:3] op_sel:[0,1,0]
	v_pk_fma_f32 v[12:13], v[126:127], v[62:63], v[12:13] op_sel:[0,1,0]
	v_pk_fma_f32 v[10:11], v[124:125], v[62:63], v[10:11] op_sel:[0,1,0]
	v_pk_fma_f32 v[8:9], v[126:127], v[70:71], v[8:9] op_sel:[0,1,0]
	v_pk_fma_f32 v[6:7], v[124:125], v[70:71], v[6:7] op_sel:[0,1,0]
	s_waitcnt vmcnt(17)
	v_pk_fma_f32 v[4:5], v[130:131], v[56:57], v[4:5] op_sel_hi:[1,0,1]
	v_pk_fma_f32 v[2:3], v[128:129], v[56:57], v[2:3] op_sel_hi:[1,0,1]
	v_pk_fma_f32 v[12:13], v[130:131], v[64:65], v[12:13] op_sel_hi:[1,0,1]
	v_pk_fma_f32 v[10:11], v[128:129], v[64:65], v[10:11] op_sel_hi:[1,0,1]
	v_pk_fma_f32 v[8:9], v[130:131], v[72:73], v[8:9] op_sel_hi:[1,0,1]
	v_pk_fma_f32 v[6:7], v[128:129], v[72:73], v[6:7] op_sel_hi:[1,0,1]
	s_waitcnt vmcnt(16)
	v_pk_fma_f32 v[4:5], v[134:135], v[80:81], v[4:5] op_sel_hi:[1,0,1]
	v_pk_fma_f32 v[2:3], v[132:133], v[80:81], v[2:3] op_sel_hi:[1,0,1]
	v_pk_fma_f32 v[12:13], v[134:135], v[82:83], v[12:13] op_sel_hi:[1,0,1]
	v_pk_fma_f32 v[10:11], v[132:133], v[82:83], v[10:11] op_sel_hi:[1,0,1]
	v_pk_fma_f32 v[8:9], v[134:135], v[84:85], v[8:9] op_sel_hi:[1,0,1]
	v_pk_fma_f32 v[6:7], v[132:133], v[84:85], v[6:7] op_sel_hi:[1,0,1]
	v_mov_b32_e32 v1, s22
	s_add_i32 s22, s22, 32
	ds_read_b128 v[50:53], v1
	ds_read_b128 v[54:57], v1 offset:16
	ds_read_b128 v[58:61], v1 offset:512
	ds_read_b128 v[62:65], v1 offset:528
	ds_read_b128 v[66:69], v1 offset:1024
	ds_read_b128 v[70:73], v1 offset:1040
	s_waitcnt lgkmcnt(5)
	v_mov_b32_e32 v74, v53
	s_waitcnt lgkmcnt(3)
	v_mov_b32_e32 v76, v61
	v_mov_b32_e32 v80, v57
	s_waitcnt lgkmcnt(1)
	v_mov_b32_e32 v78, v69
	v_mov_b32_e32 v82, v65
	s_waitcnt lgkmcnt(0)
	v_mov_b32_e32 v84, v73
	s_waitcnt vmcnt(15)
	v_pk_fma_f32 v[4:5], v[138:139], v[50:51], v[4:5] op_sel_hi:[1,0,1]
	v_pk_fma_f32 v[2:3], v[136:137], v[50:51], v[2:3] op_sel_hi:[1,0,1]
	v_pk_fma_f32 v[12:13], v[138:139], v[58:59], v[12:13] op_sel_hi:[1,0,1]
	v_pk_fma_f32 v[10:11], v[136:137], v[58:59], v[10:11] op_sel_hi:[1,0,1]
	v_pk_fma_f32 v[8:9], v[138:139], v[66:67], v[8:9] op_sel_hi:[1,0,1]
	v_pk_fma_f32 v[6:7], v[136:137], v[66:67], v[6:7] op_sel_hi:[1,0,1]
	s_waitcnt vmcnt(14)
	v_pk_fma_f32 v[2:3], v[140:141], v[50:51], v[2:3] op_sel:[0,1,0]
	v_pk_fma_f32 v[4:5], v[142:143], v[50:51], v[4:5] op_sel:[0,1,0]
	v_pk_fma_f32 v[10:11], v[140:141], v[58:59], v[10:11] op_sel:[0,1,0]
	v_pk_fma_f32 v[12:13], v[142:143], v[58:59], v[12:13] op_sel:[0,1,0]
	v_pk_fma_f32 v[6:7], v[140:141], v[66:67], v[6:7] op_sel:[0,1,0]
	v_pk_fma_f32 v[8:9], v[142:143], v[66:67], v[8:9] op_sel:[0,1,0]
	s_waitcnt vmcnt(13)
	v_pk_fma_f32 v[4:5], v[146:147], v[52:53], v[4:5] op_sel_hi:[1,0,1]
	v_pk_fma_f32 v[2:3], v[144:145], v[52:53], v[2:3] op_sel_hi:[1,0,1]
	v_pk_fma_f32 v[12:13], v[146:147], v[60:61], v[12:13] op_sel_hi:[1,0,1]
	v_pk_fma_f32 v[10:11], v[144:145], v[60:61], v[10:11] op_sel_hi:[1,0,1]
	v_pk_fma_f32 v[8:9], v[146:147], v[68:69], v[8:9] op_sel_hi:[1,0,1]
	v_pk_fma_f32 v[6:7], v[144:145], v[68:69], v[6:7] op_sel_hi:[1,0,1]
	s_waitcnt vmcnt(12)
	v_pk_fma_f32 v[4:5], v[150:151], v[74:75], v[4:5] op_sel_hi:[1,0,1]
	v_pk_fma_f32 v[2:3], v[148:149], v[74:75], v[2:3] op_sel_hi:[1,0,1]
	v_pk_fma_f32 v[12:13], v[150:151], v[76:77], v[12:13] op_sel_hi:[1,0,1]
	v_pk_fma_f32 v[10:11], v[148:149], v[76:77], v[10:11] op_sel_hi:[1,0,1]
	v_pk_fma_f32 v[8:9], v[150:151], v[78:79], v[8:9] op_sel_hi:[1,0,1]
	v_pk_fma_f32 v[6:7], v[148:149], v[78:79], v[6:7] op_sel_hi:[1,0,1]
	s_waitcnt vmcnt(11)
	v_pk_fma_f32 v[4:5], v[154:155], v[54:55], v[4:5] op_sel_hi:[1,0,1]
	v_pk_fma_f32 v[2:3], v[152:153], v[54:55], v[2:3] op_sel_hi:[1,0,1]
	v_pk_fma_f32 v[12:13], v[154:155], v[62:63], v[12:13] op_sel_hi:[1,0,1]
	v_pk_fma_f32 v[10:11], v[152:153], v[62:63], v[10:11] op_sel_hi:[1,0,1]
	v_pk_fma_f32 v[8:9], v[154:155], v[70:71], v[8:9] op_sel_hi:[1,0,1]
	v_pk_fma_f32 v[6:7], v[152:153], v[70:71], v[6:7] op_sel_hi:[1,0,1]
	s_waitcnt vmcnt(10)
	v_pk_fma_f32 v[4:5], v[158:159], v[54:55], v[4:5] op_sel:[0,1,0]
	v_pk_fma_f32 v[2:3], v[156:157], v[54:55], v[2:3] op_sel:[0,1,0]
	v_pk_fma_f32 v[12:13], v[158:159], v[62:63], v[12:13] op_sel:[0,1,0]
	v_pk_fma_f32 v[10:11], v[156:157], v[62:63], v[10:11] op_sel:[0,1,0]
	v_pk_fma_f32 v[8:9], v[158:159], v[70:71], v[8:9] op_sel:[0,1,0]
	v_pk_fma_f32 v[6:7], v[156:157], v[70:71], v[6:7] op_sel:[0,1,0]
	s_waitcnt vmcnt(9)
	v_pk_fma_f32 v[4:5], v[162:163], v[56:57], v[4:5] op_sel_hi:[1,0,1]
	v_pk_fma_f32 v[2:3], v[160:161], v[56:57], v[2:3] op_sel_hi:[1,0,1]
	v_pk_fma_f32 v[12:13], v[162:163], v[64:65], v[12:13] op_sel_hi:[1,0,1]
	v_pk_fma_f32 v[10:11], v[160:161], v[64:65], v[10:11] op_sel_hi:[1,0,1]
	v_pk_fma_f32 v[8:9], v[162:163], v[72:73], v[8:9] op_sel_hi:[1,0,1]
	v_pk_fma_f32 v[6:7], v[160:161], v[72:73], v[6:7] op_sel_hi:[1,0,1]
	s_waitcnt vmcnt(8)
	v_pk_fma_f32 v[4:5], v[166:167], v[80:81], v[4:5] op_sel_hi:[1,0,1]
	v_pk_fma_f32 v[2:3], v[164:165], v[80:81], v[2:3] op_sel_hi:[1,0,1]
	v_pk_fma_f32 v[12:13], v[166:167], v[82:83], v[12:13] op_sel_hi:[1,0,1]
	v_pk_fma_f32 v[10:11], v[164:165], v[82:83], v[10:11] op_sel_hi:[1,0,1]
	v_pk_fma_f32 v[8:9], v[166:167], v[84:85], v[8:9] op_sel_hi:[1,0,1]
	v_pk_fma_f32 v[6:7], v[164:165], v[84:85], v[6:7] op_sel_hi:[1,0,1]
	v_mov_b32_e32 v1, s22
	s_add_i32 s22, s22, 32
	ds_read_b128 v[50:53], v1
	ds_read_b128 v[54:57], v1 offset:16
	ds_read_b128 v[58:61], v1 offset:512
	ds_read_b128 v[62:65], v1 offset:528
	ds_read_b128 v[66:69], v1 offset:1024
	ds_read_b128 v[70:73], v1 offset:1040
	s_waitcnt lgkmcnt(5)
	v_mov_b32_e32 v74, v53
	s_waitcnt lgkmcnt(3)
	v_mov_b32_e32 v76, v61
	v_mov_b32_e32 v80, v57
	s_waitcnt lgkmcnt(1)
	v_mov_b32_e32 v78, v69
	v_mov_b32_e32 v82, v65
	s_waitcnt lgkmcnt(0)
	v_mov_b32_e32 v84, v73
	s_waitcnt vmcnt(7)
	v_pk_fma_f32 v[4:5], v[170:171], v[50:51], v[4:5] op_sel_hi:[1,0,1]
	v_pk_fma_f32 v[2:3], v[168:169], v[50:51], v[2:3] op_sel_hi:[1,0,1]
	v_pk_fma_f32 v[12:13], v[170:171], v[58:59], v[12:13] op_sel_hi:[1,0,1]
	v_pk_fma_f32 v[10:11], v[168:169], v[58:59], v[10:11] op_sel_hi:[1,0,1]
	v_pk_fma_f32 v[8:9], v[170:171], v[66:67], v[8:9] op_sel_hi:[1,0,1]
	v_pk_fma_f32 v[6:7], v[168:169], v[66:67], v[6:7] op_sel_hi:[1,0,1]
	s_waitcnt vmcnt(6)
	v_pk_fma_f32 v[2:3], v[172:173], v[50:51], v[2:3] op_sel:[0,1,0]
	v_pk_fma_f32 v[4:5], v[174:175], v[50:51], v[4:5] op_sel:[0,1,0]
	v_pk_fma_f32 v[10:11], v[172:173], v[58:59], v[10:11] op_sel:[0,1,0]
	v_pk_fma_f32 v[12:13], v[174:175], v[58:59], v[12:13] op_sel:[0,1,0]
	v_pk_fma_f32 v[6:7], v[172:173], v[66:67], v[6:7] op_sel:[0,1,0]
	v_pk_fma_f32 v[8:9], v[174:175], v[66:67], v[8:9] op_sel:[0,1,0]
	s_waitcnt vmcnt(5)
	v_pk_fma_f32 v[4:5], v[178:179], v[52:53], v[4:5] op_sel_hi:[1,0,1]
	v_pk_fma_f32 v[2:3], v[176:177], v[52:53], v[2:3] op_sel_hi:[1,0,1]
	v_pk_fma_f32 v[12:13], v[178:179], v[60:61], v[12:13] op_sel_hi:[1,0,1]
	v_pk_fma_f32 v[10:11], v[176:177], v[60:61], v[10:11] op_sel_hi:[1,0,1]
	v_pk_fma_f32 v[8:9], v[178:179], v[68:69], v[8:9] op_sel_hi:[1,0,1]
	v_pk_fma_f32 v[6:7], v[176:177], v[68:69], v[6:7] op_sel_hi:[1,0,1]
	s_waitcnt vmcnt(4)
	v_pk_fma_f32 v[4:5], v[182:183], v[74:75], v[4:5] op_sel_hi:[1,0,1]
	v_pk_fma_f32 v[2:3], v[180:181], v[74:75], v[2:3] op_sel_hi:[1,0,1]
	v_pk_fma_f32 v[12:13], v[182:183], v[76:77], v[12:13] op_sel_hi:[1,0,1]
	v_pk_fma_f32 v[10:11], v[180:181], v[76:77], v[10:11] op_sel_hi:[1,0,1]
	v_pk_fma_f32 v[8:9], v[182:183], v[78:79], v[8:9] op_sel_hi:[1,0,1]
	v_pk_fma_f32 v[6:7], v[180:181], v[78:79], v[6:7] op_sel_hi:[1,0,1]
	s_waitcnt vmcnt(3)
	v_pk_fma_f32 v[4:5], v[186:187], v[54:55], v[4:5] op_sel_hi:[1,0,1]
	v_pk_fma_f32 v[2:3], v[184:185], v[54:55], v[2:3] op_sel_hi:[1,0,1]
	v_pk_fma_f32 v[12:13], v[186:187], v[62:63], v[12:13] op_sel_hi:[1,0,1]
	v_pk_fma_f32 v[10:11], v[184:185], v[62:63], v[10:11] op_sel_hi:[1,0,1]
	v_pk_fma_f32 v[8:9], v[186:187], v[70:71], v[8:9] op_sel_hi:[1,0,1]
	v_pk_fma_f32 v[6:7], v[184:185], v[70:71], v[6:7] op_sel_hi:[1,0,1]
	s_waitcnt vmcnt(2)
	v_pk_fma_f32 v[4:5], v[190:191], v[54:55], v[4:5] op_sel:[0,1,0]
	v_pk_fma_f32 v[2:3], v[188:189], v[54:55], v[2:3] op_sel:[0,1,0]
	v_pk_fma_f32 v[12:13], v[190:191], v[62:63], v[12:13] op_sel:[0,1,0]
	v_pk_fma_f32 v[10:11], v[188:189], v[62:63], v[10:11] op_sel:[0,1,0]
	v_pk_fma_f32 v[8:9], v[190:191], v[70:71], v[8:9] op_sel:[0,1,0]
	v_pk_fma_f32 v[6:7], v[188:189], v[70:71], v[6:7] op_sel:[0,1,0]
	s_waitcnt vmcnt(1)
	v_pk_fma_f32 v[4:5], v[194:195], v[56:57], v[4:5] op_sel_hi:[1,0,1]
	v_pk_fma_f32 v[2:3], v[192:193], v[56:57], v[2:3] op_sel_hi:[1,0,1]
	v_pk_fma_f32 v[12:13], v[194:195], v[64:65], v[12:13] op_sel_hi:[1,0,1]
	v_pk_fma_f32 v[10:11], v[192:193], v[64:65], v[10:11] op_sel_hi:[1,0,1]
	v_pk_fma_f32 v[8:9], v[194:195], v[72:73], v[8:9] op_sel_hi:[1,0,1]
	v_pk_fma_f32 v[6:7], v[192:193], v[72:73], v[6:7] op_sel_hi:[1,0,1]
	s_waitcnt vmcnt(0)
	v_pk_fma_f32 v[4:5], v[198:199], v[80:81], v[4:5] op_sel_hi:[1,0,1]
	v_pk_fma_f32 v[2:3], v[196:197], v[80:81], v[2:3] op_sel_hi:[1,0,1]
	v_pk_fma_f32 v[12:13], v[198:199], v[82:83], v[12:13] op_sel_hi:[1,0,1]
	v_pk_fma_f32 v[10:11], v[196:197], v[82:83], v[10:11] op_sel_hi:[1,0,1]
	v_pk_fma_f32 v[8:9], v[198:199], v[84:85], v[8:9] op_sel_hi:[1,0,1]
	v_pk_fma_f32 v[6:7], v[196:197], v[84:85], v[6:7] op_sel_hi:[1,0,1]
	s_mov_b32 s4, 0x600000
	s_mov_b32 s5, 0
	s_lshl_b32 s4, s21, 5
	s_add_i32 s4, s4, s20
	s_mul_hi_i32 s5, s4, 0x24000
	s_mul_i32 s4, s4, 0x24000
	s_add_u32 s4, s60, s4
	s_addc_u32 s5, s59, s5
	s_add_u32 s0, s4, s0
	s_addc_u32 s1, s5, s1
	v_lshl_add_u64 v[14:15], v[14:15], 2, s[0:1]
	global_store_dwordx4 v[14:15], v[2:5], off
	s_add_i32 s19, s19, s62
	s_cmpk_gt_i32 s19, 0xbf
	v_add_co_u32_e32 v2, vcc, s12, v14
	s_nop 1
	v_addc_co_u32_e32 v3, vcc, 0, v15, vcc
	global_store_dwordx4 v[2:3], v[10:13], off
	v_add_co_u32_e32 v2, vcc, 0x18000, v14
	s_nop 1
	v_addc_co_u32_e32 v3, vcc, 0, v15, vcc
	global_store_dwordx4 v[2:3], v[6:9], off
	s_barrier
	s_cbranch_scc0 .LBB0_1103
